# K-loops: no priority windows inside the MFMA blocks at all (raise before the opening barrier, drop before the closing barrier)
# baseline (speedup 1.0000x reference)
; #define PG8_STAGE(bufoff, gbase, voff) do { _Pragma("unroll") for (int _i = 0; _i < 2; ++_i) \
;         __builtin_amdgcn_global_load_lds((const unsigned*)((const char*)(gbase) + (voff)[_i]), (PG8_LAS unsigned*)(lds + (bufoff) + ldsw + _i * 8192), 16, 0, 0); } while (0)
; #define PG8_LDA(dst, b, h) do { _Pragma("unroll") for (int m = 0; m < 4; ++m) _Pragma("unroll") for (int k = 0; k < 2; ++k) dst[m][k] = *(const PG8_LAS bf16x8*)(lds + PG8_SA(b, h) + aoff + m * 2048 + k * 1024); } while (0)
; #define PG8_LDB(dst, b, h) do { _Pragma("unroll") for (int n = 0; n < 2; ++n) _Pragma("unroll") for (int k = 0; k < 2; ++k) dst[n][k] = *(const PG8_LAS bf16x8*)(lds + PG8_SB(b, h) + boff + n * 2048 + k * 1024); } while (0)
; #define PG8_MMA(ai, bj, At, Bt) do { __builtin_amdgcn_s_setprio(1); _Pragma("unroll") for (int m = 0; m < 4; ++m) _Pragma("unroll") for (int n = 0; n < 2; ++n) _Pragma("unroll") for (int k = 0; k < 2; ++k) \
;         acc[ai][bj][m][n] = __builtin_amdgcn_mfma_f32_16x16x32_bf16(Bt[n][k], At[m][k], acc[ai][bj][m][n], 0, 0, 0); __builtin_amdgcn_s_setprio(0); } while (0)
; #define PG8_WAIT_V(n) asm volatile("s_waitcnt vmcnt(" #n ")" ::: "memory")
; #define PG8_WAIT_L(n) asm volatile("s_waitcnt lgkmcnt(" #n ")" ::: "memory")
; #define PG8_BAR __builtin_amdgcn_s_barrier()
; #define PG8_SCHED __builtin_amdgcn_sched_barrier(0)
; template <class Epi, class Sched, bool ALIGN_EPI = false, bool SP2 = false>
; __device__ __forceinline__ void gemm_phase(PG8_LAS unsigned char* lds, const Gemm g, const Sched& S, const Epi& E) {
;     ...
;             const bool last = (t == nt - 2);
;             const char* a1 = cA + (size_t)(t + 1) * kstep;
;             const char* a2 = last ? nA : cA + (size_t)(t + 2) * kstep; const char* b2 = last ? nB : cB + (size_t)(t + 2) * kstep;
;             const char* a3 = a2 + kstep; const char* b3 = b2 + kstep;
;             if (last && has_next) S.a_ready(nxt);
;             if constexpr (SP2) {
;             PG8_LDB(B0, 0, 0); PG8_LDB(B1, 0, 1); PG8_SCHED; PG8_LDA(At, 0, 0); PG8_STAGE(PG8_SA(1, 1), a1 + hstep, voffA);
;             PG8_WAIT_V(8); PG8_WAIT_L(0); PG8_BAR; PG8_MMA(0, 0, At, B0); PG8_MMA(0, 1, At, B1); PG8_BAR; PG8_SCHED;
;             PG8_LDA(At, 0, 1); PG8_STAGE(PG8_SB(0, 0), b2, voffB); PG8_STAGE(PG8_SB(0, 1), b2 + hstep, voffB); PG8_STAGE(PG8_SA(0, 0), a2, voffA);
.LBB0_36:
	s_add_u32 s18, s58, 0xffe00080
	s_addc_u32 s19, s59, -1
	s_add_i32 s47, 0, 0x10000
	s_cmpk_eq_i32 s46, 0x7c
	s_cselect_b32 s63, s45, s19
	s_cselect_b32 s62, s73, s18
	v_add_u32_e32 v160, s47, v143
	s_cselect_b32 s19, s37, s79
	s_cselect_b32 s18, s84, s78
	s_add_i32 s80, 0, 0x14000
	ds_read_b128 v[156:159], v160
	ds_read_b128 v[164:167], v160 offset:1024
	ds_read_b128 v[168:171], v160 offset:2048
	ds_read_b128 v[172:175], v160 offset:3072
	v_add_u32_e32 v160, s80, v143
	ds_read_b128 v[176:179], v160
	ds_read_b128 v[180:183], v160 offset:1024
	ds_read_b128 v[184:187], v160 offset:2048
	ds_read_b128 v[204:207], v160 offset:3072
	v_lshl_add_u64 v[160:161], s[58:59], 0, v[152:153]
	s_add_i32 m0, s5, 0xc000
	ds_read_b128 v[208:211], v163
	ds_read_b128 v[212:215], v163 offset:1024
	ds_read_b128 v[216:219], v163 offset:2048
	ds_read_b128 v[220:223], v163 offset:3072
	ds_read_b128 v[224:227], v163 offset:4096
	ds_read_b128 v[228:231], v163 offset:5120
	ds_read_b128 v[232:235], v163 offset:6144
	ds_read_b128 v[236:239], v163 offset:7168
	global_load_lds_dwordx4 v[160:161], off
	v_lshl_add_u64 v[160:161], s[58:59], 0, v[154:155]
	s_add_i32 m0, s5, 0xe000
	s_nop 0
	global_load_lds_dwordx4 v[160:161], off
	s_nop 0
	s_waitcnt vmcnt(8)
	s_waitcnt lgkmcnt(0)
	s_setprio 1
	s_barrier
	v_mfma_f32_16x16x32_bf16 v[126:129], v[156:159], v[208:211], v[126:129]
	v_mfma_f32_16x16x32_bf16 v[122:125], v[168:171], v[208:211], v[122:125]
	v_mfma_f32_16x16x32_bf16 v[110:113], v[156:159], v[216:219], v[110:113]
	v_mfma_f32_16x16x32_bf16 v[106:109], v[168:171], v[216:219], v[106:109]
	v_mfma_f32_16x16x32_bf16 v[94:97], v[156:159], v[224:227], v[94:97]
	v_mfma_f32_16x16x32_bf16 v[90:93], v[168:171], v[224:227], v[90:93]
	v_mfma_f32_16x16x32_bf16 v[78:81], v[156:159], v[232:235], v[78:81]
	v_mfma_f32_16x16x32_bf16 v[74:77], v[168:171], v[232:235], v[74:77]
	v_mfma_f32_16x16x32_bf16 v[126:129], v[164:167], v[212:215], v[126:129]
	v_mfma_f32_16x16x32_bf16 v[122:125], v[172:175], v[212:215], v[122:125]
	v_mfma_f32_16x16x32_bf16 v[110:113], v[164:167], v[220:223], v[110:113]
	v_mfma_f32_16x16x32_bf16 v[106:109], v[172:175], v[220:223], v[106:109]
	v_mfma_f32_16x16x32_bf16 v[94:97], v[164:167], v[228:231], v[94:97]
	v_mfma_f32_16x16x32_bf16 v[90:93], v[172:175], v[228:231], v[90:93]
	v_mfma_f32_16x16x32_bf16 v[78:81], v[164:167], v[236:239], v[78:81]
	v_mfma_f32_16x16x32_bf16 v[74:77], v[172:175], v[236:239], v[74:77]
	v_mfma_f32_16x16x32_bf16 v[118:121], v[176:179], v[208:211], v[118:121]
	v_mfma_f32_16x16x32_bf16 v[114:117], v[184:187], v[208:211], v[114:117]
	v_mfma_f32_16x16x32_bf16 v[102:105], v[176:179], v[216:219], v[102:105]
	v_mfma_f32_16x16x32_bf16 v[98:101], v[184:187], v[216:219], v[98:101]
	v_mfma_f32_16x16x32_bf16 v[86:89], v[176:179], v[224:227], v[86:89]
	v_mfma_f32_16x16x32_bf16 v[82:85], v[184:187], v[224:227], v[82:85]
	v_mfma_f32_16x16x32_bf16 v[70:73], v[176:179], v[232:235], v[70:73]
	v_mfma_f32_16x16x32_bf16 v[66:69], v[184:187], v[232:235], v[66:69]
	v_mfma_f32_16x16x32_bf16 v[118:121], v[180:183], v[212:215], v[118:121]
	v_mfma_f32_16x16x32_bf16 v[114:117], v[204:207], v[212:215], v[114:117]
	v_mfma_f32_16x16x32_bf16 v[102:105], v[180:183], v[220:223], v[102:105]
	v_mfma_f32_16x16x32_bf16 v[98:101], v[204:207], v[220:223], v[98:101]
	v_mfma_f32_16x16x32_bf16 v[86:89], v[180:183], v[228:231], v[86:89]
	v_mfma_f32_16x16x32_bf16 v[82:85], v[204:207], v[228:231], v[82:85]
	v_mfma_f32_16x16x32_bf16 v[70:73], v[180:183], v[236:239], v[70:73]
	v_mfma_f32_16x16x32_bf16 v[66:69], v[204:207], v[236:239], v[66:69]
	s_setprio 0
	s_barrier
	s_add_i32 s47, s47, s4
	v_lshl_add_u64 v[160:161], s[18:19], 0, v[148:149]
	s_mov_b32 m0, s47
	ds_read_b128 v[208:211], v163 offset:16384
	ds_read_b128 v[212:215], v163 offset:17408
	ds_read_b128 v[216:219], v163 offset:18432
	ds_read_b128 v[220:223], v163 offset:19456
	ds_read_b128 v[224:227], v163 offset:20480
	ds_read_b128 v[228:231], v163 offset:21504
	ds_read_b128 v[232:235], v163 offset:22528
	ds_read_b128 v[236:239], v163 offset:23552
	global_load_lds_dwordx4 v[160:161], off
	s_add_i32 m0, s47, 0x2000
	s_add_u32 s76, s18, 0x200000
	v_lshl_add_u64 v[240:241], s[18:19], 0, v[144:145]
	s_addc_u32 s77, s19, 0
	s_add_i32 s47, s80, s4
	global_load_lds_dwordx4 v[240:241], off
	v_lshl_add_u64 v[242:243], s[76:77], 0, v[148:149]
	s_mov_b32 m0, s47
	v_lshl_add_u64 v[244:245], s[62:63], 0, v[146:147]
	global_load_lds_dwordx4 v[242:243], off
	v_lshl_add_u64 v[242:243], s[76:77], 0, v[144:145]
	s_add_i32 m0, s47, 0x2000
	s_nop 0
	global_load_lds_dwordx4 v[242:243], off
	v_lshl_add_u64 v[242:243], s[62:63], 0, v[150:151]
	s_mov_b32 m0, s5
	s_nop 0
	global_load_lds_dwordx4 v[242:243], off
	s_mov_b32 m0, s30
	s_nop 0
	global_load_lds_dwordx4 v[244:245], off
	s_waitcnt vmcnt(8)
	s_waitcnt lgkmcnt(0)
	s_setprio 1
	s_barrier
; #define PG8_STAGE(bufoff, gbase, voff) do { _Pragma("unroll") for (int _i = 0; _i < 2; ++_i) \
;         __builtin_amdgcn_global_load_lds((const unsigned*)((const char*)(gbase) + (voff)[_i]), (PG8_LAS unsigned*)(lds + (bufoff) + ldsw + _i * 8192), 16, 0, 0); } while (0)
; #define PG8_LDA(dst, b, h) do { _Pragma("unroll") for (int m = 0; m < 4; ++m) _Pragma("unroll") for (int k = 0; k < 2; ++k) dst[m][k] = *(const PG8_LAS bf16x8*)(lds + PG8_SA(b, h) + aoff + m * 2048 + k * 1024); } while (0)
; #define PG8_LDB(dst, b, h) do { _Pragma("unroll") for (int n = 0; n < 2; ++n) _Pragma("unroll") for (int k = 0; k < 2; ++k) dst[n][k] = *(const PG8_LAS bf16x8*)(lds + PG8_SB(b, h) + boff + n * 2048 + k * 1024); } while (0)
; #define PG8_MMA(ai, bj, At, Bt) do { __builtin_amdgcn_s_setprio(1); _Pragma("unroll") for (int m = 0; m < 4; ++m) _Pragma("unroll") for (int n = 0; n < 2; ++n) _Pragma("unroll") for (int k = 0; k < 2; ++k) \
;         acc[ai][bj][m][n] = __builtin_amdgcn_mfma_f32_16x16x32_bf16(Bt[n][k], At[m][k], acc[ai][bj][m][n], 0, 0, 0); __builtin_amdgcn_s_setprio(0); } while (0)
; #define PG8_WAIT_V(n) asm volatile("s_waitcnt vmcnt(" #n ")" ::: "memory")
; #define PG8_WAIT_L(n) asm volatile("s_waitcnt lgkmcnt(" #n ")" ::: "memory")
; #define PG8_BAR __builtin_amdgcn_s_barrier()
; #define PG8_SCHED __builtin_amdgcn_sched_barrier(0)
; template <class Epi, class Sched, bool ALIGN_EPI = false, bool SP2 = false>
; __device__ __forceinline__ void gemm_phase(PG8_LAS unsigned char* lds, const Gemm g, const Sched& S, const Epi& E) {
;     ...
;             PG8_WAIT_V(8); PG8_WAIT_L(0); PG8_BAR; PG8_MMA(1, 0, At, B0); PG8_MMA(1, 1, At, B1); PG8_BAR; PG8_SCHED;
;             PG8_LDB(B0, 1, 0); PG8_LDB(B1, 1, 1); PG8_SCHED; PG8_LDA(At, 1, 0); PG8_STAGE(PG8_SA(0, 1), a2 + hstep, voffA);
;             PG8_WAIT_V(8); PG8_WAIT_L(0); PG8_BAR; PG8_MMA(0, 0, At, B0); PG8_MMA(0, 1, At, B1); PG8_BAR; PG8_SCHED;
	v_mfma_f32_16x16x32_bf16 v[62:65], v[156:159], v[208:211], v[62:65]
	v_mfma_f32_16x16x32_bf16 v[58:61], v[168:171], v[208:211], v[58:61]
	v_mfma_f32_16x16x32_bf16 v[46:49], v[156:159], v[216:219], v[46:49]
	v_mfma_f32_16x16x32_bf16 v[42:45], v[168:171], v[216:219], v[42:45]
	v_mfma_f32_16x16x32_bf16 v[30:33], v[156:159], v[224:227], v[30:33]
	v_mfma_f32_16x16x32_bf16 v[26:29], v[168:171], v[224:227], v[26:29]
	v_mfma_f32_16x16x32_bf16 v[14:17], v[156:159], v[232:235], v[14:17]
	v_mfma_f32_16x16x32_bf16 v[10:13], v[168:171], v[232:235], v[10:13]
	v_mfma_f32_16x16x32_bf16 v[62:65], v[164:167], v[212:215], v[62:65]
	v_mfma_f32_16x16x32_bf16 v[58:61], v[172:175], v[212:215], v[58:61]
	v_mfma_f32_16x16x32_bf16 v[46:49], v[164:167], v[220:223], v[46:49]
	v_mfma_f32_16x16x32_bf16 v[42:45], v[172:175], v[220:223], v[42:45]
	v_mfma_f32_16x16x32_bf16 v[30:33], v[164:167], v[228:231], v[30:33]
	v_mfma_f32_16x16x32_bf16 v[26:29], v[172:175], v[228:231], v[26:29]
	v_mfma_f32_16x16x32_bf16 v[14:17], v[164:167], v[236:239], v[14:17]
	v_mfma_f32_16x16x32_bf16 v[10:13], v[172:175], v[236:239], v[10:13]
	v_mfma_f32_16x16x32_bf16 v[54:57], v[176:179], v[208:211], v[54:57]
	v_mfma_f32_16x16x32_bf16 v[50:53], v[184:187], v[208:211], v[50:53]
	v_mfma_f32_16x16x32_bf16 v[38:41], v[176:179], v[216:219], v[38:41]
	v_mfma_f32_16x16x32_bf16 v[34:37], v[184:187], v[216:219], v[34:37]
	v_mfma_f32_16x16x32_bf16 v[22:25], v[176:179], v[224:227], v[22:25]
	v_mfma_f32_16x16x32_bf16 v[18:21], v[184:187], v[224:227], v[18:21]
	v_mfma_f32_16x16x32_bf16 v[6:9], v[176:179], v[232:235], v[6:9]
	v_mfma_f32_16x16x32_bf16 v[2:5], v[184:187], v[232:235], v[2:5]
	v_mfma_f32_16x16x32_bf16 v[54:57], v[180:183], v[212:215], v[54:57]
	v_mfma_f32_16x16x32_bf16 v[50:53], v[204:207], v[212:215], v[50:53]
	v_mfma_f32_16x16x32_bf16 v[38:41], v[180:183], v[220:223], v[38:41]
	v_mfma_f32_16x16x32_bf16 v[34:37], v[204:207], v[220:223], v[34:37]
	v_mfma_f32_16x16x32_bf16 v[22:25], v[180:183], v[228:231], v[22:25]
	v_mfma_f32_16x16x32_bf16 v[18:21], v[204:207], v[228:231], v[18:21]
	v_mfma_f32_16x16x32_bf16 v[6:9], v[180:183], v[236:239], v[6:9]
	v_mfma_f32_16x16x32_bf16 v[2:5], v[204:207], v[236:239], v[2:5]
	s_setprio 0
	s_barrier
	s_add_i32 s47, 0, 0x18000
	s_add_i32 s76, 0, 0x1c000
	v_add_u32_e32 v172, s47, v143
	v_add_u32_e32 v203, s76, v143
	ds_read_b128 v[156:159], v172
	ds_read_b128 v[164:167], v172 offset:1024
	ds_read_b128 v[168:171], v172 offset:2048
	ds_read_b128 v[172:175], v172 offset:3072
	ds_read_b128 v[176:179], v203
	ds_read_b128 v[180:183], v203 offset:1024
	ds_read_b128 v[184:187], v203 offset:2048
	ds_read_b128 v[204:207], v203 offset:3072
	s_add_u32 s62, s62, 0x200000
	s_addc_u32 s63, s63, 0
	s_mov_b32 m0, s57
	v_lshl_add_u64 v[246:247], s[62:63], 0, v[150:151]
	ds_read_b128 v[208:211], v163 offset:32768
	ds_read_b128 v[212:215], v163 offset:33792
	ds_read_b128 v[216:219], v163 offset:34816
	ds_read_b128 v[220:223], v163 offset:35840
	ds_read_b128 v[224:227], v163 offset:36864
	ds_read_b128 v[228:231], v163 offset:37888
	ds_read_b128 v[232:235], v163 offset:38912
	ds_read_b128 v[236:239], v163 offset:39936
	global_load_lds_dwordx4 v[246:247], off
	v_lshl_add_u64 v[246:247], s[62:63], 0, v[146:147]
	s_mov_b32 m0, s67
	s_nop 0
	global_load_lds_dwordx4 v[246:247], off
	s_waitcnt vmcnt(8)
	s_waitcnt lgkmcnt(0)
	s_setprio 1
	s_barrier
	v_mfma_f32_16x16x32_bf16 v[126:129], v[156:159], v[208:211], v[126:129]
	v_mfma_f32_16x16x32_bf16 v[122:125], v[168:171], v[208:211], v[122:125]
	v_mfma_f32_16x16x32_bf16 v[110:113], v[156:159], v[216:219], v[110:113]
	v_mfma_f32_16x16x32_bf16 v[106:109], v[168:171], v[216:219], v[106:109]
	v_mfma_f32_16x16x32_bf16 v[94:97], v[156:159], v[224:227], v[94:97]
	v_mfma_f32_16x16x32_bf16 v[90:93], v[168:171], v[224:227], v[90:93]
	v_mfma_f32_16x16x32_bf16 v[78:81], v[156:159], v[232:235], v[78:81]
	v_mfma_f32_16x16x32_bf16 v[74:77], v[168:171], v[232:235], v[74:77]
	v_mfma_f32_16x16x32_bf16 v[126:129], v[164:167], v[212:215], v[126:129]
	v_mfma_f32_16x16x32_bf16 v[122:125], v[172:175], v[212:215], v[122:125]
	v_mfma_f32_16x16x32_bf16 v[110:113], v[164:167], v[220:223], v[110:113]
	v_mfma_f32_16x16x32_bf16 v[106:109], v[172:175], v[220:223], v[106:109]
	v_mfma_f32_16x16x32_bf16 v[94:97], v[164:167], v[228:231], v[94:97]
	v_mfma_f32_16x16x32_bf16 v[90:93], v[172:175], v[228:231], v[90:93]
	v_mfma_f32_16x16x32_bf16 v[78:81], v[164:167], v[236:239], v[78:81]
	v_mfma_f32_16x16x32_bf16 v[74:77], v[172:175], v[236:239], v[74:77]
	v_mfma_f32_16x16x32_bf16 v[118:121], v[176:179], v[208:211], v[118:121]
	v_mfma_f32_16x16x32_bf16 v[114:117], v[184:187], v[208:211], v[114:117]
	v_mfma_f32_16x16x32_bf16 v[102:105], v[176:179], v[216:219], v[102:105]
	v_mfma_f32_16x16x32_bf16 v[98:101], v[184:187], v[216:219], v[98:101]
	v_mfma_f32_16x16x32_bf16 v[86:89], v[176:179], v[224:227], v[86:89]
	v_mfma_f32_16x16x32_bf16 v[82:85], v[184:187], v[224:227], v[82:85]
	v_mfma_f32_16x16x32_bf16 v[70:73], v[176:179], v[232:235], v[70:73]
	v_mfma_f32_16x16x32_bf16 v[66:69], v[184:187], v[232:235], v[66:69]
	v_mfma_f32_16x16x32_bf16 v[118:121], v[180:183], v[212:215], v[118:121]
	v_mfma_f32_16x16x32_bf16 v[114:117], v[204:207], v[212:215], v[114:117]
	v_mfma_f32_16x16x32_bf16 v[102:105], v[180:183], v[220:223], v[102:105]
	v_mfma_f32_16x16x32_bf16 v[98:101], v[204:207], v[220:223], v[98:101]
	v_mfma_f32_16x16x32_bf16 v[86:89], v[180:183], v[228:231], v[86:89]
	v_mfma_f32_16x16x32_bf16 v[82:85], v[204:207], v[228:231], v[82:85]
	v_mfma_f32_16x16x32_bf16 v[70:73], v[180:183], v[236:239], v[70:73]
	v_mfma_f32_16x16x32_bf16 v[66:69], v[204:207], v[236:239], v[66:69]
	s_setprio 0
	s_barrier
; #define PG8_STAGE(bufoff, gbase, voff) do { _Pragma("unroll") for (int _i = 0; _i < 2; ++_i) \
;         __builtin_amdgcn_global_load_lds((const unsigned*)((const char*)(gbase) + (voff)[_i]), (PG8_LAS unsigned*)(lds + (bufoff) + ldsw + _i * 8192), 16, 0, 0); } while (0)
; #define PG8_LDA(dst, b, h) do { _Pragma("unroll") for (int m = 0; m < 4; ++m) _Pragma("unroll") for (int k = 0; k < 2; ++k) dst[m][k] = *(const PG8_LAS bf16x8*)(lds + PG8_SA(b, h) + aoff + m * 2048 + k * 1024); } while (0)
; #define PG8_MMA(ai, bj, At, Bt) do { __builtin_amdgcn_s_setprio(1); _Pragma("unroll") for (int m = 0; m < 4; ++m) _Pragma("unroll") for (int n = 0; n < 2; ++n) _Pragma("unroll") for (int k = 0; k < 2; ++k) \
;         acc[ai][bj][m][n] = __builtin_amdgcn_mfma_f32_16x16x32_bf16(Bt[n][k], At[m][k], acc[ai][bj][m][n], 0, 0, 0); __builtin_amdgcn_s_setprio(0); } while (0)
; #define PG8_WAIT_V(n) asm volatile("s_waitcnt vmcnt(" #n ")" ::: "memory")
; #define PG8_WAIT_L(n) asm volatile("s_waitcnt lgkmcnt(" #n ")" ::: "memory")
; #define PG8_BAR __builtin_amdgcn_s_barrier()
; #define PG8_SCHED __builtin_amdgcn_sched_barrier(0)
; template <class Epi, class Sched, bool ALIGN_EPI = false, bool SP2 = false>
; __device__ __forceinline__ void gemm_phase(PG8_LAS unsigned char* lds, const Gemm g, const Sched& S, const Epi& E) {
;     ...
;             PG8_LDA(At, 1, 1); PG8_STAGE(PG8_SB(1, 0), b3, voffB); PG8_STAGE(PG8_SB(1, 1), b3 + hstep, voffB); PG8_STAGE(PG8_SA(1, 0), a3, voffA);
;             PG8_WAIT_V(8); PG8_WAIT_L(0); PG8_BAR; PG8_MMA(1, 0, At, B0); PG8_MMA(1, 1, At, B1); PG8_BAR; PG8_SCHED;
	s_add_i32 s47, s47, s4
	v_lshl_add_u64 v[160:161], v[160:161], 0, s[68:69]
	s_mov_b32 m0, s47
	ds_read_b128 v[208:211], v163 offset:49152
	ds_read_b128 v[212:215], v163 offset:50176
	ds_read_b128 v[216:219], v163 offset:51200
	ds_read_b128 v[220:223], v163 offset:52224
	ds_read_b128 v[224:227], v163 offset:53248
	ds_read_b128 v[228:231], v163 offset:54272
	ds_read_b128 v[232:235], v163 offset:55296
	ds_read_b128 v[236:239], v163 offset:56320
	global_load_lds_dwordx4 v[160:161], off
	s_add_i32 m0, s47, 0x2000
	s_add_u32 s18, s18, 0x200080
	v_lshl_add_u64 v[160:161], v[240:241], 0, s[68:69]
	s_addc_u32 s19, s19, 0
	s_add_i32 s47, s76, s4
	global_load_lds_dwordx4 v[160:161], off
	v_lshl_add_u64 v[160:161], s[18:19], 0, v[148:149]
	s_mov_b32 m0, s47
	s_nop 0
	global_load_lds_dwordx4 v[160:161], off
	v_lshl_add_u64 v[160:161], s[18:19], 0, v[144:145]
	s_add_i32 m0, s47, 0x2000
	s_nop 0
	global_load_lds_dwordx4 v[160:161], off
	v_lshl_add_u64 v[160:161], v[242:243], 0, s[68:69]
	s_mov_b32 m0, s1
	s_nop 0
	global_load_lds_dwordx4 v[160:161], off
	v_lshl_add_u64 v[160:161], v[244:245], 0, s[68:69]
	s_mov_b32 m0, s60
	s_nop 0
	global_load_lds_dwordx4 v[160:161], off
	s_nop 0
	s_waitcnt vmcnt(8)
	s_waitcnt lgkmcnt(0)
	s_setprio 1
	s_barrier
	v_mfma_f32_16x16x32_bf16 v[62:65], v[156:159], v[208:211], v[62:65]
	v_mfma_f32_16x16x32_bf16 v[58:61], v[168:171], v[208:211], v[58:61]
	v_mfma_f32_16x16x32_bf16 v[46:49], v[156:159], v[216:219], v[46:49]
	v_mfma_f32_16x16x32_bf16 v[42:45], v[168:171], v[216:219], v[42:45]
	v_mfma_f32_16x16x32_bf16 v[30:33], v[156:159], v[224:227], v[30:33]
	v_mfma_f32_16x16x32_bf16 v[26:29], v[168:171], v[224:227], v[26:29]
	v_mfma_f32_16x16x32_bf16 v[14:17], v[156:159], v[232:235], v[14:17]
	v_mfma_f32_16x16x32_bf16 v[10:13], v[168:171], v[232:235], v[10:13]
	v_mfma_f32_16x16x32_bf16 v[62:65], v[164:167], v[212:215], v[62:65]
	v_mfma_f32_16x16x32_bf16 v[58:61], v[172:175], v[212:215], v[58:61]
	v_mfma_f32_16x16x32_bf16 v[46:49], v[164:167], v[220:223], v[46:49]
	v_mfma_f32_16x16x32_bf16 v[42:45], v[172:175], v[220:223], v[42:45]
	v_mfma_f32_16x16x32_bf16 v[30:33], v[164:167], v[228:231], v[30:33]
	v_mfma_f32_16x16x32_bf16 v[26:29], v[172:175], v[228:231], v[26:29]
	v_mfma_f32_16x16x32_bf16 v[14:17], v[164:167], v[236:239], v[14:17]
	v_mfma_f32_16x16x32_bf16 v[10:13], v[172:175], v[236:239], v[10:13]
	v_mfma_f32_16x16x32_bf16 v[54:57], v[176:179], v[208:211], v[54:57]
	v_mfma_f32_16x16x32_bf16 v[50:53], v[184:187], v[208:211], v[50:53]
	v_mfma_f32_16x16x32_bf16 v[38:41], v[176:179], v[216:219], v[38:41]
	v_mfma_f32_16x16x32_bf16 v[34:37], v[184:187], v[216:219], v[34:37]
	v_mfma_f32_16x16x32_bf16 v[22:25], v[176:179], v[224:227], v[22:25]
	v_mfma_f32_16x16x32_bf16 v[18:21], v[184:187], v[224:227], v[18:21]
	v_mfma_f32_16x16x32_bf16 v[6:9], v[176:179], v[232:235], v[6:9]
	v_mfma_f32_16x16x32_bf16 v[2:5], v[184:187], v[232:235], v[2:5]
	v_mfma_f32_16x16x32_bf16 v[54:57], v[180:183], v[212:215], v[54:57]
	v_mfma_f32_16x16x32_bf16 v[50:53], v[204:207], v[212:215], v[50:53]
	v_mfma_f32_16x16x32_bf16 v[38:41], v[180:183], v[220:223], v[38:41]
	v_mfma_f32_16x16x32_bf16 v[34:37], v[204:207], v[220:223], v[34:37]
	v_mfma_f32_16x16x32_bf16 v[22:25], v[180:183], v[228:231], v[22:25]
	v_mfma_f32_16x16x32_bf16 v[18:21], v[204:207], v[228:231], v[18:21]
	v_mfma_f32_16x16x32_bf16 v[6:9], v[180:183], v[236:239], v[6:9]
	v_mfma_f32_16x16x32_bf16 v[2:5], v[204:207], v[236:239], v[2:5]
	s_setprio 0
	s_barrier
	s_add_i32 s46, s46, 2
	s_add_u32 s58, s58, 0x100
	s_addc_u32 s59, s59, 0
	s_add_u32 s78, s78, 0x100
	s_addc_u32 s79, s79, 0
	s_cmpk_gt_u32 s46, 0x7d
	s_cbranch_scc0 .LBB0_36
	s_and_b64 vcc, exec, s[12:13]
	s_cbranch_vccz .LBB0_39
	s_barrier

; #define PG8_STAGE(bufoff, gbase, voff) do { _Pragma("unroll") for (int _i = 0; _i < 2; ++_i) \
;         __builtin_amdgcn_global_load_lds((const unsigned*)((const char*)(gbase) + (voff)[_i]), (PG8_LAS unsigned*)(lds + (bufoff) + ldsw + _i * 8192), 16, 0, 0); } while (0)
; #define PG8_LDA(dst, b, h) do { _Pragma("unroll") for (int m = 0; m < 4; ++m) _Pragma("unroll") for (int k = 0; k < 2; ++k) dst[m][k] = *(const PG8_LAS bf16x8*)(lds + PG8_SA(b, h) + aoff + m * 2048 + k * 1024); } while (0)
; #define PG8_LDB(dst, b, h) do { _Pragma("unroll") for (int n = 0; n < 2; ++n) _Pragma("unroll") for (int k = 0; k < 2; ++k) dst[n][k] = *(const PG8_LAS bf16x8*)(lds + PG8_SB(b, h) + boff + n * 2048 + k * 1024); } while (0)
; #define PG8_MMA(ai, bj, At, Bt) do { __builtin_amdgcn_s_setprio(1); _Pragma("unroll") for (int m = 0; m < 4; ++m) _Pragma("unroll") for (int n = 0; n < 2; ++n) _Pragma("unroll") for (int k = 0; k < 2; ++k) \
;         acc[ai][bj][m][n] = __builtin_amdgcn_mfma_f32_16x16x32_bf16(Bt[n][k], At[m][k], acc[ai][bj][m][n], 0, 0, 0); __builtin_amdgcn_s_setprio(0); } while (0)
; #define PG8_WAIT_V(n) asm volatile("s_waitcnt vmcnt(" #n ")" ::: "memory")
; #define PG8_WAIT_L(n) asm volatile("s_waitcnt lgkmcnt(" #n ")" ::: "memory")
; #define PG8_BAR __builtin_amdgcn_s_barrier()
; #define PG8_SCHED __builtin_amdgcn_sched_barrier(0)
; template <class Epi, class Sched, bool ALIGN_EPI = false, bool SP2 = false>
; __device__ __forceinline__ void gemm_phase(PG8_LAS unsigned char* lds, const Gemm g, const Sched& S, const Epi& E) {
;     ...
;             const bool last = (t == nt - 2);
;             const char* a1 = cA + (size_t)(t + 1) * kstep;
;             const char* a2 = last ? nA : cA + (size_t)(t + 2) * kstep; const char* b2 = last ? nB : cB + (size_t)(t + 2) * kstep;
;             const char* a3 = a2 + kstep; const char* b3 = b2 + kstep;
;             if (last && has_next) S.a_ready(nxt);
;             if constexpr (SP2) {
;             PG8_LDB(B0, 0, 0); PG8_LDB(B1, 0, 1); PG8_SCHED; PG8_LDA(At, 0, 0); PG8_STAGE(PG8_SA(1, 1), a1 + hstep, voffA);
;             PG8_WAIT_V(8); PG8_WAIT_L(0); PG8_BAR; PG8_MMA(0, 0, At, B0); PG8_MMA(0, 1, At, B1); PG8_BAR; PG8_SCHED;
;             PG8_LDA(At, 0, 1); PG8_STAGE(PG8_SB(0, 0), b2, voffB); PG8_STAGE(PG8_SB(0, 1), b2 + hstep, voffB); PG8_STAGE(PG8_SA(0, 0), a2, voffA);
.LBB0_76:
	s_add_u32 s18, s0, 0xfff80080
	s_addc_u32 s19, s1, -1
	s_add_i32 s47, 0, 0x10000
	s_cmp_eq_u32 s46, 28
	s_cselect_b32 s59, s60, s19
	s_cselect_b32 s58, s73, s18
	v_add_u32_e32 v158, s47, v143
	s_cselect_b32 s19, s45, s79
	s_cselect_b32 s18, s84, s78
	s_add_i32 s80, 0, 0x14000
	ds_read_b128 v[162:165], v158
	ds_read_b128 v[166:169], v158 offset:1024
	ds_read_b128 v[170:173], v158 offset:2048
	ds_read_b128 v[174:177], v158 offset:3072
	v_add_u32_e32 v158, s80, v143
	ds_read_b128 v[178:181], v158
	ds_read_b128 v[182:185], v158 offset:1024
	ds_read_b128 v[204:207], v158 offset:2048
	ds_read_b128 v[208:211], v158 offset:3072
	v_lshl_add_u64 v[158:159], s[0:1], 0, v[154:155]
	s_add_i32 m0, s62, 0xc000
	ds_read_b128 v[212:215], v161
	ds_read_b128 v[216:219], v161 offset:1024
	ds_read_b128 v[220:223], v161 offset:2048
	ds_read_b128 v[224:227], v161 offset:3072
	ds_read_b128 v[228:231], v161 offset:4096
	ds_read_b128 v[232:235], v161 offset:5120
	ds_read_b128 v[236:239], v161 offset:6144
	ds_read_b128 v[240:243], v161 offset:7168
	global_load_lds_dwordx4 v[158:159], off
	v_lshl_add_u64 v[158:159], s[0:1], 0, v[156:157]
	s_add_i32 m0, s62, 0xe000
	s_nop 0
	global_load_lds_dwordx4 v[158:159], off
	s_nop 0
	s_waitcnt vmcnt(8)
	s_waitcnt lgkmcnt(0)
	s_setprio 1
	s_barrier
	v_mfma_f32_16x16x32_bf16 v[126:129], v[162:165], v[212:215], v[126:129]
	v_mfma_f32_16x16x32_bf16 v[122:125], v[170:173], v[212:215], v[122:125]
	v_mfma_f32_16x16x32_bf16 v[110:113], v[162:165], v[220:223], v[110:113]
	v_mfma_f32_16x16x32_bf16 v[106:109], v[170:173], v[220:223], v[106:109]
	v_mfma_f32_16x16x32_bf16 v[94:97], v[162:165], v[228:231], v[94:97]
	v_mfma_f32_16x16x32_bf16 v[90:93], v[170:173], v[228:231], v[90:93]
	v_mfma_f32_16x16x32_bf16 v[78:81], v[162:165], v[236:239], v[78:81]
	v_mfma_f32_16x16x32_bf16 v[74:77], v[170:173], v[236:239], v[74:77]
	v_mfma_f32_16x16x32_bf16 v[126:129], v[166:169], v[216:219], v[126:129]
	v_mfma_f32_16x16x32_bf16 v[122:125], v[174:177], v[216:219], v[122:125]
	v_mfma_f32_16x16x32_bf16 v[110:113], v[166:169], v[224:227], v[110:113]
	v_mfma_f32_16x16x32_bf16 v[106:109], v[174:177], v[224:227], v[106:109]
	v_mfma_f32_16x16x32_bf16 v[94:97], v[166:169], v[232:235], v[94:97]
	v_mfma_f32_16x16x32_bf16 v[90:93], v[174:177], v[232:235], v[90:93]
	v_mfma_f32_16x16x32_bf16 v[78:81], v[166:169], v[240:243], v[78:81]
	v_mfma_f32_16x16x32_bf16 v[74:77], v[174:177], v[240:243], v[74:77]
	v_mfma_f32_16x16x32_bf16 v[118:121], v[178:181], v[212:215], v[118:121]
	v_mfma_f32_16x16x32_bf16 v[114:117], v[204:207], v[212:215], v[114:117]
	v_mfma_f32_16x16x32_bf16 v[102:105], v[178:181], v[220:223], v[102:105]
	v_mfma_f32_16x16x32_bf16 v[98:101], v[204:207], v[220:223], v[98:101]
	v_mfma_f32_16x16x32_bf16 v[86:89], v[178:181], v[228:231], v[86:89]
	v_mfma_f32_16x16x32_bf16 v[82:85], v[204:207], v[228:231], v[82:85]
	v_mfma_f32_16x16x32_bf16 v[70:73], v[178:181], v[236:239], v[70:73]
	v_mfma_f32_16x16x32_bf16 v[66:69], v[204:207], v[236:239], v[66:69]
	v_mfma_f32_16x16x32_bf16 v[118:121], v[182:185], v[216:219], v[118:121]
	v_mfma_f32_16x16x32_bf16 v[114:117], v[208:211], v[216:219], v[114:117]
	v_mfma_f32_16x16x32_bf16 v[102:105], v[182:185], v[224:227], v[102:105]
	v_mfma_f32_16x16x32_bf16 v[98:101], v[208:211], v[224:227], v[98:101]
	v_mfma_f32_16x16x32_bf16 v[86:89], v[182:185], v[232:235], v[86:89]
	v_mfma_f32_16x16x32_bf16 v[82:85], v[208:211], v[232:235], v[82:85]
	v_mfma_f32_16x16x32_bf16 v[70:73], v[182:185], v[240:243], v[70:73]
	v_mfma_f32_16x16x32_bf16 v[66:69], v[208:211], v[240:243], v[66:69]
	s_setprio 0
	s_barrier
	s_add_i32 s47, s47, s54
	v_lshl_add_u64 v[158:159], s[18:19], 0, v[148:149]
	s_mov_b32 m0, s47
	ds_read_b128 v[212:215], v161 offset:16384
	ds_read_b128 v[216:219], v161 offset:17408
	ds_read_b128 v[220:223], v161 offset:18432
	ds_read_b128 v[224:227], v161 offset:19456
	ds_read_b128 v[228:231], v161 offset:20480
	ds_read_b128 v[232:235], v161 offset:21504
	ds_read_b128 v[236:239], v161 offset:22528
	ds_read_b128 v[240:243], v161 offset:23552
	global_load_lds_dwordx4 v[158:159], off
	s_add_i32 m0, s47, 0x2000
	s_add_u32 s76, s18, 0x80000
	v_lshl_add_u64 v[186:187], s[18:19], 0, v[144:145]
	s_addc_u32 s77, s19, 0
	s_add_i32 s47, s80, s54
	global_load_lds_dwordx4 v[186:187], off
	v_lshl_add_u64 v[244:245], s[76:77], 0, v[148:149]
	s_mov_b32 m0, s47
	v_lshl_add_u64 v[246:247], s[58:59], 0, v[146:147]
	global_load_lds_dwordx4 v[244:245], off
	v_lshl_add_u64 v[244:245], s[76:77], 0, v[144:145]
	s_add_i32 m0, s47, 0x2000
	s_nop 0
	global_load_lds_dwordx4 v[244:245], off
	v_lshl_add_u64 v[244:245], s[58:59], 0, v[150:151]
	s_mov_b32 m0, s62
	s_nop 0
	global_load_lds_dwordx4 v[244:245], off
	s_mov_b32 m0, s63
	s_nop 0
	global_load_lds_dwordx4 v[246:247], off
	s_waitcnt vmcnt(8)
	s_waitcnt lgkmcnt(0)
	s_setprio 1
	s_barrier
; #define PG8_STAGE(bufoff, gbase, voff) do { _Pragma("unroll") for (int _i = 0; _i < 2; ++_i) \
;         __builtin_amdgcn_global_load_lds((const unsigned*)((const char*)(gbase) + (voff)[_i]), (PG8_LAS unsigned*)(lds + (bufoff) + ldsw + _i * 8192), 16, 0, 0); } while (0)
; #define PG8_LDA(dst, b, h) do { _Pragma("unroll") for (int m = 0; m < 4; ++m) _Pragma("unroll") for (int k = 0; k < 2; ++k) dst[m][k] = *(const PG8_LAS bf16x8*)(lds + PG8_SA(b, h) + aoff + m * 2048 + k * 1024); } while (0)
; #define PG8_LDB(dst, b, h) do { _Pragma("unroll") for (int n = 0; n < 2; ++n) _Pragma("unroll") for (int k = 0; k < 2; ++k) dst[n][k] = *(const PG8_LAS bf16x8*)(lds + PG8_SB(b, h) + boff + n * 2048 + k * 1024); } while (0)
; #define PG8_MMA(ai, bj, At, Bt) do { __builtin_amdgcn_s_setprio(1); _Pragma("unroll") for (int m = 0; m < 4; ++m) _Pragma("unroll") for (int n = 0; n < 2; ++n) _Pragma("unroll") for (int k = 0; k < 2; ++k) \
;         acc[ai][bj][m][n] = __builtin_amdgcn_mfma_f32_16x16x32_bf16(Bt[n][k], At[m][k], acc[ai][bj][m][n], 0, 0, 0); __builtin_amdgcn_s_setprio(0); } while (0)
; #define PG8_WAIT_V(n) asm volatile("s_waitcnt vmcnt(" #n ")" ::: "memory")
; #define PG8_WAIT_L(n) asm volatile("s_waitcnt lgkmcnt(" #n ")" ::: "memory")
; #define PG8_BAR __builtin_amdgcn_s_barrier()
; #define PG8_SCHED __builtin_amdgcn_sched_barrier(0)
; template <class Epi, class Sched, bool ALIGN_EPI = false, bool SP2 = false>
; __device__ __forceinline__ void gemm_phase(PG8_LAS unsigned char* lds, const Gemm g, const Sched& S, const Epi& E) {
;     ...
;             PG8_WAIT_V(8); PG8_WAIT_L(0); PG8_BAR; PG8_MMA(1, 0, At, B0); PG8_MMA(1, 1, At, B1); PG8_BAR; PG8_SCHED;
;             PG8_LDB(B0, 1, 0); PG8_LDB(B1, 1, 1); PG8_SCHED; PG8_LDA(At, 1, 0); PG8_STAGE(PG8_SA(0, 1), a2 + hstep, voffA);
;             PG8_WAIT_V(8); PG8_WAIT_L(0); PG8_BAR; PG8_MMA(0, 0, At, B0); PG8_MMA(0, 1, At, B1); PG8_BAR; PG8_SCHED;
	v_mfma_f32_16x16x32_bf16 v[62:65], v[162:165], v[212:215], v[62:65]
	v_mfma_f32_16x16x32_bf16 v[58:61], v[170:173], v[212:215], v[58:61]
	v_mfma_f32_16x16x32_bf16 v[46:49], v[162:165], v[220:223], v[46:49]
	v_mfma_f32_16x16x32_bf16 v[42:45], v[170:173], v[220:223], v[42:45]
	v_mfma_f32_16x16x32_bf16 v[30:33], v[162:165], v[228:231], v[30:33]
	v_mfma_f32_16x16x32_bf16 v[26:29], v[170:173], v[228:231], v[26:29]
	v_mfma_f32_16x16x32_bf16 v[14:17], v[162:165], v[236:239], v[14:17]
	v_mfma_f32_16x16x32_bf16 v[10:13], v[170:173], v[236:239], v[10:13]
	v_mfma_f32_16x16x32_bf16 v[62:65], v[166:169], v[216:219], v[62:65]
	v_mfma_f32_16x16x32_bf16 v[58:61], v[174:177], v[216:219], v[58:61]
	v_mfma_f32_16x16x32_bf16 v[46:49], v[166:169], v[224:227], v[46:49]
	v_mfma_f32_16x16x32_bf16 v[42:45], v[174:177], v[224:227], v[42:45]
	v_mfma_f32_16x16x32_bf16 v[30:33], v[166:169], v[232:235], v[30:33]
	v_mfma_f32_16x16x32_bf16 v[26:29], v[174:177], v[232:235], v[26:29]
	v_mfma_f32_16x16x32_bf16 v[14:17], v[166:169], v[240:243], v[14:17]
	v_mfma_f32_16x16x32_bf16 v[10:13], v[174:177], v[240:243], v[10:13]
	v_mfma_f32_16x16x32_bf16 v[54:57], v[178:181], v[212:215], v[54:57]
	v_mfma_f32_16x16x32_bf16 v[50:53], v[204:207], v[212:215], v[50:53]
	v_mfma_f32_16x16x32_bf16 v[38:41], v[178:181], v[220:223], v[38:41]
	v_mfma_f32_16x16x32_bf16 v[34:37], v[204:207], v[220:223], v[34:37]
	v_mfma_f32_16x16x32_bf16 v[22:25], v[178:181], v[228:231], v[22:25]
	v_mfma_f32_16x16x32_bf16 v[18:21], v[204:207], v[228:231], v[18:21]
	v_mfma_f32_16x16x32_bf16 v[6:9], v[178:181], v[236:239], v[6:9]
	v_mfma_f32_16x16x32_bf16 v[2:5], v[204:207], v[236:239], v[2:5]
	v_mfma_f32_16x16x32_bf16 v[54:57], v[182:185], v[216:219], v[54:57]
	v_mfma_f32_16x16x32_bf16 v[50:53], v[208:211], v[216:219], v[50:53]
	v_mfma_f32_16x16x32_bf16 v[38:41], v[182:185], v[224:227], v[38:41]
	v_mfma_f32_16x16x32_bf16 v[34:37], v[208:211], v[224:227], v[34:37]
	v_mfma_f32_16x16x32_bf16 v[22:25], v[182:185], v[232:235], v[22:25]
	v_mfma_f32_16x16x32_bf16 v[18:21], v[208:211], v[232:235], v[18:21]
	v_mfma_f32_16x16x32_bf16 v[6:9], v[182:185], v[240:243], v[6:9]
	v_mfma_f32_16x16x32_bf16 v[2:5], v[208:211], v[240:243], v[2:5]
	s_setprio 0
	s_barrier
	s_add_i32 s47, 0, 0x18000
	s_add_i32 s76, 0, 0x1c000
	v_add_u32_e32 v174, s47, v143
	v_add_u32_e32 v203, s76, v143
	ds_read_b128 v[162:165], v174
	ds_read_b128 v[166:169], v174 offset:1024
	ds_read_b128 v[170:173], v174 offset:2048
	ds_read_b128 v[174:177], v174 offset:3072
	ds_read_b128 v[178:181], v203
	ds_read_b128 v[182:185], v203 offset:1024
	ds_read_b128 v[204:207], v203 offset:2048
	ds_read_b128 v[208:211], v203 offset:3072
	s_add_u32 s58, s58, 0x80000
	s_addc_u32 s59, s59, 0
	s_mov_b32 m0, s67
	v_lshl_add_u64 v[248:249], s[58:59], 0, v[150:151]
	ds_read_b128 v[212:215], v161 offset:32768
	ds_read_b128 v[216:219], v161 offset:33792
	ds_read_b128 v[220:223], v161 offset:34816
	ds_read_b128 v[224:227], v161 offset:35840
	ds_read_b128 v[228:231], v161 offset:36864
	ds_read_b128 v[232:235], v161 offset:37888
	ds_read_b128 v[236:239], v161 offset:38912
	ds_read_b128 v[240:243], v161 offset:39936
	global_load_lds_dwordx4 v[248:249], off
	v_lshl_add_u64 v[248:249], s[58:59], 0, v[146:147]
	s_mov_b32 m0, s4
	s_nop 0
	global_load_lds_dwordx4 v[248:249], off
	s_waitcnt vmcnt(8)
	s_waitcnt lgkmcnt(0)
	s_setprio 1
	s_barrier
	v_mfma_f32_16x16x32_bf16 v[126:129], v[162:165], v[212:215], v[126:129]
	v_mfma_f32_16x16x32_bf16 v[122:125], v[170:173], v[212:215], v[122:125]
	v_mfma_f32_16x16x32_bf16 v[110:113], v[162:165], v[220:223], v[110:113]
	v_mfma_f32_16x16x32_bf16 v[106:109], v[170:173], v[220:223], v[106:109]
	v_mfma_f32_16x16x32_bf16 v[94:97], v[162:165], v[228:231], v[94:97]
	v_mfma_f32_16x16x32_bf16 v[90:93], v[170:173], v[228:231], v[90:93]
	v_mfma_f32_16x16x32_bf16 v[78:81], v[162:165], v[236:239], v[78:81]
	v_mfma_f32_16x16x32_bf16 v[74:77], v[170:173], v[236:239], v[74:77]
	v_mfma_f32_16x16x32_bf16 v[126:129], v[166:169], v[216:219], v[126:129]
	v_mfma_f32_16x16x32_bf16 v[122:125], v[174:177], v[216:219], v[122:125]
	v_mfma_f32_16x16x32_bf16 v[110:113], v[166:169], v[224:227], v[110:113]
	v_mfma_f32_16x16x32_bf16 v[106:109], v[174:177], v[224:227], v[106:109]
	v_mfma_f32_16x16x32_bf16 v[94:97], v[166:169], v[232:235], v[94:97]
	v_mfma_f32_16x16x32_bf16 v[90:93], v[174:177], v[232:235], v[90:93]
	v_mfma_f32_16x16x32_bf16 v[78:81], v[166:169], v[240:243], v[78:81]
	v_mfma_f32_16x16x32_bf16 v[74:77], v[174:177], v[240:243], v[74:77]
	v_mfma_f32_16x16x32_bf16 v[118:121], v[178:181], v[212:215], v[118:121]
	v_mfma_f32_16x16x32_bf16 v[114:117], v[204:207], v[212:215], v[114:117]
	v_mfma_f32_16x16x32_bf16 v[102:105], v[178:181], v[220:223], v[102:105]
	v_mfma_f32_16x16x32_bf16 v[98:101], v[204:207], v[220:223], v[98:101]
	v_mfma_f32_16x16x32_bf16 v[86:89], v[178:181], v[228:231], v[86:89]
	v_mfma_f32_16x16x32_bf16 v[82:85], v[204:207], v[228:231], v[82:85]
	v_mfma_f32_16x16x32_bf16 v[70:73], v[178:181], v[236:239], v[70:73]
	v_mfma_f32_16x16x32_bf16 v[66:69], v[204:207], v[236:239], v[66:69]
	v_mfma_f32_16x16x32_bf16 v[118:121], v[182:185], v[216:219], v[118:121]
	v_mfma_f32_16x16x32_bf16 v[114:117], v[208:211], v[216:219], v[114:117]
	v_mfma_f32_16x16x32_bf16 v[102:105], v[182:185], v[224:227], v[102:105]
	v_mfma_f32_16x16x32_bf16 v[98:101], v[208:211], v[224:227], v[98:101]
	v_mfma_f32_16x16x32_bf16 v[86:89], v[182:185], v[232:235], v[86:89]
	v_mfma_f32_16x16x32_bf16 v[82:85], v[208:211], v[232:235], v[82:85]
	v_mfma_f32_16x16x32_bf16 v[70:73], v[182:185], v[240:243], v[70:73]
	v_mfma_f32_16x16x32_bf16 v[66:69], v[208:211], v[240:243], v[66:69]
	s_setprio 0
	s_barrier
; #define PG8_STAGE(bufoff, gbase, voff) do { _Pragma("unroll") for (int _i = 0; _i < 2; ++_i) \
;         __builtin_amdgcn_global_load_lds((const unsigned*)((const char*)(gbase) + (voff)[_i]), (PG8_LAS unsigned*)(lds + (bufoff) + ldsw + _i * 8192), 16, 0, 0); } while (0)
; #define PG8_LDA(dst, b, h) do { _Pragma("unroll") for (int m = 0; m < 4; ++m) _Pragma("unroll") for (int k = 0; k < 2; ++k) dst[m][k] = *(const PG8_LAS bf16x8*)(lds + PG8_SA(b, h) + aoff + m * 2048 + k * 1024); } while (0)
; #define PG8_MMA(ai, bj, At, Bt) do { __builtin_amdgcn_s_setprio(1); _Pragma("unroll") for (int m = 0; m < 4; ++m) _Pragma("unroll") for (int n = 0; n < 2; ++n) _Pragma("unroll") for (int k = 0; k < 2; ++k) \
;         acc[ai][bj][m][n] = __builtin_amdgcn_mfma_f32_16x16x32_bf16(Bt[n][k], At[m][k], acc[ai][bj][m][n], 0, 0, 0); __builtin_amdgcn_s_setprio(0); } while (0)
; #define PG8_WAIT_V(n) asm volatile("s_waitcnt vmcnt(" #n ")" ::: "memory")
; #define PG8_WAIT_L(n) asm volatile("s_waitcnt lgkmcnt(" #n ")" ::: "memory")
; #define PG8_BAR __builtin_amdgcn_s_barrier()
; #define PG8_SCHED __builtin_amdgcn_sched_barrier(0)
; template <class Epi, class Sched, bool ALIGN_EPI = false, bool SP2 = false>
; __device__ __forceinline__ void gemm_phase(PG8_LAS unsigned char* lds, const Gemm g, const Sched& S, const Epi& E) {
;     ...
;             PG8_LDA(At, 1, 1); PG8_STAGE(PG8_SB(1, 0), b3, voffB); PG8_STAGE(PG8_SB(1, 1), b3 + hstep, voffB); PG8_STAGE(PG8_SA(1, 0), a3, voffA);
;             PG8_WAIT_V(8); PG8_WAIT_L(0); PG8_BAR; PG8_MMA(1, 0, At, B0); PG8_MMA(1, 1, At, B1); PG8_BAR; PG8_SCHED;
	s_add_i32 s47, s47, s54
	v_lshl_add_u64 v[158:159], v[158:159], 0, s[68:69]
	s_mov_b32 m0, s47
	ds_read_b128 v[212:215], v161 offset:49152
	ds_read_b128 v[216:219], v161 offset:50176
	ds_read_b128 v[220:223], v161 offset:51200
	ds_read_b128 v[224:227], v161 offset:52224
	ds_read_b128 v[228:231], v161 offset:53248
	ds_read_b128 v[232:235], v161 offset:54272
	ds_read_b128 v[236:239], v161 offset:55296
	ds_read_b128 v[240:243], v161 offset:56320
	global_load_lds_dwordx4 v[158:159], off
	s_add_i32 m0, s47, 0x2000
	s_add_u32 s18, s18, 0x80080
	v_lshl_add_u64 v[158:159], v[186:187], 0, s[68:69]
	s_addc_u32 s19, s19, 0
	s_add_i32 s47, s76, s54
	global_load_lds_dwordx4 v[158:159], off
	v_lshl_add_u64 v[158:159], s[18:19], 0, v[148:149]
	s_mov_b32 m0, s47
	s_nop 0
	global_load_lds_dwordx4 v[158:159], off
	v_lshl_add_u64 v[158:159], s[18:19], 0, v[144:145]
	s_add_i32 m0, s47, 0x2000
	s_nop 0
	global_load_lds_dwordx4 v[158:159], off
	v_lshl_add_u64 v[158:159], v[244:245], 0, s[68:69]
	s_mov_b32 m0, s5
	s_nop 0
	global_load_lds_dwordx4 v[158:159], off
	v_lshl_add_u64 v[158:159], v[246:247], 0, s[68:69]
	s_mov_b32 m0, s57
	s_nop 0
	global_load_lds_dwordx4 v[158:159], off
	s_nop 0
	s_waitcnt vmcnt(8)
	s_waitcnt lgkmcnt(0)
	s_setprio 1
	s_barrier
	v_mfma_f32_16x16x32_bf16 v[62:65], v[162:165], v[212:215], v[62:65]
	v_mfma_f32_16x16x32_bf16 v[58:61], v[170:173], v[212:215], v[58:61]
	v_mfma_f32_16x16x32_bf16 v[46:49], v[162:165], v[220:223], v[46:49]
	v_mfma_f32_16x16x32_bf16 v[42:45], v[170:173], v[220:223], v[42:45]
	v_mfma_f32_16x16x32_bf16 v[30:33], v[162:165], v[228:231], v[30:33]
	v_mfma_f32_16x16x32_bf16 v[26:29], v[170:173], v[228:231], v[26:29]
	v_mfma_f32_16x16x32_bf16 v[14:17], v[162:165], v[236:239], v[14:17]
	v_mfma_f32_16x16x32_bf16 v[10:13], v[170:173], v[236:239], v[10:13]
	v_mfma_f32_16x16x32_bf16 v[62:65], v[166:169], v[216:219], v[62:65]
	v_mfma_f32_16x16x32_bf16 v[58:61], v[174:177], v[216:219], v[58:61]
	v_mfma_f32_16x16x32_bf16 v[46:49], v[166:169], v[224:227], v[46:49]
	v_mfma_f32_16x16x32_bf16 v[42:45], v[174:177], v[224:227], v[42:45]
	v_mfma_f32_16x16x32_bf16 v[30:33], v[166:169], v[232:235], v[30:33]
	v_mfma_f32_16x16x32_bf16 v[26:29], v[174:177], v[232:235], v[26:29]
	v_mfma_f32_16x16x32_bf16 v[14:17], v[166:169], v[240:243], v[14:17]
	v_mfma_f32_16x16x32_bf16 v[10:13], v[174:177], v[240:243], v[10:13]
	v_mfma_f32_16x16x32_bf16 v[54:57], v[178:181], v[212:215], v[54:57]
	v_mfma_f32_16x16x32_bf16 v[50:53], v[204:207], v[212:215], v[50:53]
	v_mfma_f32_16x16x32_bf16 v[38:41], v[178:181], v[220:223], v[38:41]
	v_mfma_f32_16x16x32_bf16 v[34:37], v[204:207], v[220:223], v[34:37]
	v_mfma_f32_16x16x32_bf16 v[22:25], v[178:181], v[228:231], v[22:25]
	v_mfma_f32_16x16x32_bf16 v[18:21], v[204:207], v[228:231], v[18:21]
	v_mfma_f32_16x16x32_bf16 v[6:9], v[178:181], v[236:239], v[6:9]
	v_mfma_f32_16x16x32_bf16 v[2:5], v[204:207], v[236:239], v[2:5]
	v_mfma_f32_16x16x32_bf16 v[54:57], v[182:185], v[216:219], v[54:57]
	v_mfma_f32_16x16x32_bf16 v[50:53], v[208:211], v[216:219], v[50:53]
	v_mfma_f32_16x16x32_bf16 v[38:41], v[182:185], v[224:227], v[38:41]
	v_mfma_f32_16x16x32_bf16 v[34:37], v[208:211], v[224:227], v[34:37]
	v_mfma_f32_16x16x32_bf16 v[22:25], v[182:185], v[232:235], v[22:25]
	v_mfma_f32_16x16x32_bf16 v[18:21], v[208:211], v[232:235], v[18:21]
	v_mfma_f32_16x16x32_bf16 v[6:9], v[182:185], v[240:243], v[6:9]
	v_mfma_f32_16x16x32_bf16 v[2:5], v[208:211], v[240:243], v[2:5]
	s_setprio 0
	s_barrier
	s_add_i32 s46, s46, 2
	s_add_u32 s0, s0, 0x100
	s_addc_u32 s1, s1, 0
	s_add_u32 s78, s78, 0x100
	s_addc_u32 s79, s79, 0
	s_cmp_gt_u32 s46, 29
	s_cbranch_scc0 .LBB0_76
	s_and_b64 vcc, exec, s[42:43]
	s_cbranch_vccz .LBB0_79
	s_barrier

; #define PG8_STAGE(bufoff, gbase, voff) do { _Pragma("unroll") for (int _i = 0; _i < 2; ++_i) \
;         __builtin_amdgcn_global_load_lds((const unsigned*)((const char*)(gbase) + (voff)[_i]), (PG8_LAS unsigned*)(lds + (bufoff) + ldsw + _i * 8192), 16, 0, 0); } while (0)
; #define PG8_LDA(dst, b, h) do { _Pragma("unroll") for (int m = 0; m < 4; ++m) _Pragma("unroll") for (int k = 0; k < 2; ++k) dst[m][k] = *(const PG8_LAS bf16x8*)(lds + PG8_SA(b, h) + aoff + m * 2048 + k * 1024); } while (0)
; #define PG8_LDB(dst, b, h) do { _Pragma("unroll") for (int n = 0; n < 2; ++n) _Pragma("unroll") for (int k = 0; k < 2; ++k) dst[n][k] = *(const PG8_LAS bf16x8*)(lds + PG8_SB(b, h) + boff + n * 2048 + k * 1024); } while (0)
; #define PG8_MMA(ai, bj, At, Bt) do { __builtin_amdgcn_s_setprio(1); _Pragma("unroll") for (int m = 0; m < 4; ++m) _Pragma("unroll") for (int n = 0; n < 2; ++n) _Pragma("unroll") for (int k = 0; k < 2; ++k) \
;         acc[ai][bj][m][n] = __builtin_amdgcn_mfma_f32_16x16x32_bf16(Bt[n][k], At[m][k], acc[ai][bj][m][n], 0, 0, 0); __builtin_amdgcn_s_setprio(0); } while (0)
; #define PG8_WAIT_V(n) asm volatile("s_waitcnt vmcnt(" #n ")" ::: "memory")
; #define PG8_WAIT_L(n) asm volatile("s_waitcnt lgkmcnt(" #n ")" ::: "memory")
; #define PG8_BAR __builtin_amdgcn_s_barrier()
; #define PG8_SCHED __builtin_amdgcn_sched_barrier(0)
; template <class Epi, class Sched, bool ALIGN_EPI = false, bool SP2 = false>
; __device__ __forceinline__ void gemm_phase(PG8_LAS unsigned char* lds, const Gemm g, const Sched& S, const Epi& E) {
;     ...
;             const bool last = (t == nt - 2);
;             const char* a1 = cA + (size_t)(t + 1) * kstep;
;             const char* a2 = last ? nA : cA + (size_t)(t + 2) * kstep; const char* b2 = last ? nB : cB + (size_t)(t + 2) * kstep;
;             const char* a3 = a2 + kstep; const char* b3 = b2 + kstep;
;             if (last && has_next) S.a_ready(nxt);
;             if constexpr (SP2) {
;             PG8_LDB(B0, 0, 0); PG8_LDB(B1, 0, 1); PG8_SCHED; PG8_LDA(At, 0, 0); PG8_STAGE(PG8_SA(1, 1), a1 + hstep, voffA);
;             PG8_WAIT_V(8); PG8_WAIT_L(0); PG8_BAR; PG8_MMA(0, 0, At, B0); PG8_MMA(0, 1, At, B1); PG8_BAR; PG8_SCHED;
;             PG8_LDA(At, 0, 1); PG8_STAGE(PG8_SB(0, 0), b2, voffB); PG8_STAGE(PG8_SB(0, 1), b2 + hstep, voffB); PG8_STAGE(PG8_SA(0, 0), a2, voffA);
.LBB0_98:
	s_add_u32 s40, vcc_lo, 0xfff80080
	s_addc_u32 s41, vcc_hi, -1
	s_add_i32 s47, 0, 0x10000
	s_cmp_eq_u32 s46, 28
	s_cselect_b32 s59, s97, s41
	s_cselect_b32 s58, s84, s40
	s_cselect_b32 s41, s85, s79
	s_cselect_b32 s40, s95, s78
	s_add_i32 s80, 0, 0x14000
	v_add_u32_e32 v170, s47, v143
	v_add_u32_e32 v186, s80, v143
	ds_read_b128 v[156:159], v170
	ds_read_b128 v[162:165], v170 offset:1024
	ds_read_b128 v[166:169], v170 offset:2048
	ds_read_b128 v[170:173], v170 offset:3072
	ds_read_b128 v[174:177], v186
	ds_read_b128 v[178:181], v186 offset:1024
	ds_read_b128 v[182:185], v186 offset:2048
	ds_read_b128 v[204:207], v186 offset:3072
	v_lshl_add_u64 v[186:187], vcc, 0, v[152:153]
	s_add_i32 m0, s5, 0xc000
	ds_read_b128 v[208:211], v161
	ds_read_b128 v[212:215], v161 offset:1024
	ds_read_b128 v[216:219], v161 offset:2048
	ds_read_b128 v[220:223], v161 offset:3072
	ds_read_b128 v[224:227], v161 offset:4096
	ds_read_b128 v[228:231], v161 offset:5120
	ds_read_b128 v[232:235], v161 offset:6144
	ds_read_b128 v[236:239], v161 offset:7168
	global_load_lds_dwordx4 v[186:187], off
	v_lshl_add_u64 v[186:187], vcc, 0, v[154:155]
	s_add_i32 m0, s5, 0xe000
	s_nop 0
	global_load_lds_dwordx4 v[186:187], off
	s_waitcnt vmcnt(8)
	s_waitcnt lgkmcnt(0)
	s_setprio 1
	s_barrier
	v_mfma_f32_16x16x32_bf16 v[126:129], v[156:159], v[208:211], v[126:129]
	v_mfma_f32_16x16x32_bf16 v[122:125], v[166:169], v[208:211], v[122:125]
	v_mfma_f32_16x16x32_bf16 v[110:113], v[156:159], v[216:219], v[110:113]
	v_mfma_f32_16x16x32_bf16 v[106:109], v[166:169], v[216:219], v[106:109]
	v_mfma_f32_16x16x32_bf16 v[94:97], v[156:159], v[224:227], v[94:97]
	v_mfma_f32_16x16x32_bf16 v[90:93], v[166:169], v[224:227], v[90:93]
	v_mfma_f32_16x16x32_bf16 v[78:81], v[156:159], v[232:235], v[78:81]
	v_mfma_f32_16x16x32_bf16 v[74:77], v[166:169], v[232:235], v[74:77]
	v_mfma_f32_16x16x32_bf16 v[126:129], v[162:165], v[212:215], v[126:129]
	v_mfma_f32_16x16x32_bf16 v[122:125], v[170:173], v[212:215], v[122:125]
	v_mfma_f32_16x16x32_bf16 v[110:113], v[162:165], v[220:223], v[110:113]
	v_mfma_f32_16x16x32_bf16 v[106:109], v[170:173], v[220:223], v[106:109]
	v_mfma_f32_16x16x32_bf16 v[94:97], v[162:165], v[228:231], v[94:97]
	v_mfma_f32_16x16x32_bf16 v[90:93], v[170:173], v[228:231], v[90:93]
	v_mfma_f32_16x16x32_bf16 v[78:81], v[162:165], v[236:239], v[78:81]
	v_mfma_f32_16x16x32_bf16 v[74:77], v[170:173], v[236:239], v[74:77]
	v_mfma_f32_16x16x32_bf16 v[118:121], v[174:177], v[208:211], v[118:121]
	v_mfma_f32_16x16x32_bf16 v[114:117], v[182:185], v[208:211], v[114:117]
	v_mfma_f32_16x16x32_bf16 v[102:105], v[174:177], v[216:219], v[102:105]
	v_mfma_f32_16x16x32_bf16 v[98:101], v[182:185], v[216:219], v[98:101]
	v_mfma_f32_16x16x32_bf16 v[86:89], v[174:177], v[224:227], v[86:89]
	v_mfma_f32_16x16x32_bf16 v[82:85], v[182:185], v[224:227], v[82:85]
	v_mfma_f32_16x16x32_bf16 v[70:73], v[174:177], v[232:235], v[70:73]
	v_mfma_f32_16x16x32_bf16 v[66:69], v[182:185], v[232:235], v[66:69]
	v_mfma_f32_16x16x32_bf16 v[118:121], v[178:181], v[212:215], v[118:121]
	v_mfma_f32_16x16x32_bf16 v[114:117], v[204:207], v[212:215], v[114:117]
	v_mfma_f32_16x16x32_bf16 v[102:105], v[178:181], v[220:223], v[102:105]
	v_mfma_f32_16x16x32_bf16 v[98:101], v[204:207], v[220:223], v[98:101]
	v_mfma_f32_16x16x32_bf16 v[86:89], v[178:181], v[228:231], v[86:89]
	v_mfma_f32_16x16x32_bf16 v[82:85], v[204:207], v[228:231], v[82:85]
	v_mfma_f32_16x16x32_bf16 v[70:73], v[178:181], v[236:239], v[70:73]
	v_mfma_f32_16x16x32_bf16 v[66:69], v[204:207], v[236:239], v[66:69]
	s_setprio 0
	s_barrier
	s_add_i32 s47, s47, s4
	v_lshl_add_u64 v[186:187], s[40:41], 0, v[148:149]
	s_mov_b32 m0, s47
	ds_read_b128 v[208:211], v161 offset:16384
	ds_read_b128 v[212:215], v161 offset:17408
	ds_read_b128 v[216:219], v161 offset:18432
	ds_read_b128 v[220:223], v161 offset:19456
	ds_read_b128 v[224:227], v161 offset:20480
	ds_read_b128 v[228:231], v161 offset:21504
	ds_read_b128 v[232:235], v161 offset:22528
	ds_read_b128 v[236:239], v161 offset:23552
	global_load_lds_dwordx4 v[186:187], off
	s_add_i32 m0, s47, 0x2000
	s_add_u32 s76, s40, 0x80000
	v_lshl_add_u64 v[240:241], s[40:41], 0, v[144:145]
	s_addc_u32 s77, s41, 0
	s_add_i32 s47, s80, s4
	global_load_lds_dwordx4 v[240:241], off
	v_lshl_add_u64 v[242:243], s[76:77], 0, v[148:149]
	s_mov_b32 m0, s47
	v_lshl_add_u64 v[244:245], s[58:59], 0, v[146:147]
	global_load_lds_dwordx4 v[242:243], off
	v_lshl_add_u64 v[242:243], s[76:77], 0, v[144:145]
	s_add_i32 m0, s47, 0x2000
	s_nop 0
	global_load_lds_dwordx4 v[242:243], off
	v_lshl_add_u64 v[242:243], s[58:59], 0, v[150:151]
	s_mov_b32 m0, s5
	s_nop 0
	global_load_lds_dwordx4 v[242:243], off
	s_mov_b32 m0, s30
	s_nop 0
	global_load_lds_dwordx4 v[244:245], off
	s_waitcnt vmcnt(8)
	s_waitcnt lgkmcnt(0)
	s_setprio 1
	s_barrier
; #define PG8_STAGE(bufoff, gbase, voff) do { _Pragma("unroll") for (int _i = 0; _i < 2; ++_i) \
;         __builtin_amdgcn_global_load_lds((const unsigned*)((const char*)(gbase) + (voff)[_i]), (PG8_LAS unsigned*)(lds + (bufoff) + ldsw + _i * 8192), 16, 0, 0); } while (0)
; #define PG8_LDA(dst, b, h) do { _Pragma("unroll") for (int m = 0; m < 4; ++m) _Pragma("unroll") for (int k = 0; k < 2; ++k) dst[m][k] = *(const PG8_LAS bf16x8*)(lds + PG8_SA(b, h) + aoff + m * 2048 + k * 1024); } while (0)
; #define PG8_LDB(dst, b, h) do { _Pragma("unroll") for (int n = 0; n < 2; ++n) _Pragma("unroll") for (int k = 0; k < 2; ++k) dst[n][k] = *(const PG8_LAS bf16x8*)(lds + PG8_SB(b, h) + boff + n * 2048 + k * 1024); } while (0)
; #define PG8_MMA(ai, bj, At, Bt) do { __builtin_amdgcn_s_setprio(1); _Pragma("unroll") for (int m = 0; m < 4; ++m) _Pragma("unroll") for (int n = 0; n < 2; ++n) _Pragma("unroll") for (int k = 0; k < 2; ++k) \
;         acc[ai][bj][m][n] = __builtin_amdgcn_mfma_f32_16x16x32_bf16(Bt[n][k], At[m][k], acc[ai][bj][m][n], 0, 0, 0); __builtin_amdgcn_s_setprio(0); } while (0)
; #define PG8_WAIT_V(n) asm volatile("s_waitcnt vmcnt(" #n ")" ::: "memory")
; #define PG8_WAIT_L(n) asm volatile("s_waitcnt lgkmcnt(" #n ")" ::: "memory")
; #define PG8_BAR __builtin_amdgcn_s_barrier()
; #define PG8_SCHED __builtin_amdgcn_sched_barrier(0)
; template <class Epi, class Sched, bool ALIGN_EPI = false, bool SP2 = false>
; __device__ __forceinline__ void gemm_phase(PG8_LAS unsigned char* lds, const Gemm g, const Sched& S, const Epi& E) {
;     ...
;             PG8_WAIT_V(8); PG8_WAIT_L(0); PG8_BAR; PG8_MMA(1, 0, At, B0); PG8_MMA(1, 1, At, B1); PG8_BAR; PG8_SCHED;
;             PG8_LDB(B0, 1, 0); PG8_LDB(B1, 1, 1); PG8_SCHED; PG8_LDA(At, 1, 0); PG8_STAGE(PG8_SA(0, 1), a2 + hstep, voffA);
;             PG8_WAIT_V(8); PG8_WAIT_L(0); PG8_BAR; PG8_MMA(0, 0, At, B0); PG8_MMA(0, 1, At, B1); PG8_BAR; PG8_SCHED;
	v_mfma_f32_16x16x32_bf16 v[62:65], v[156:159], v[208:211], v[62:65]
	v_mfma_f32_16x16x32_bf16 v[58:61], v[166:169], v[208:211], v[58:61]
	v_mfma_f32_16x16x32_bf16 v[46:49], v[156:159], v[216:219], v[46:49]
	v_mfma_f32_16x16x32_bf16 v[42:45], v[166:169], v[216:219], v[42:45]
	v_mfma_f32_16x16x32_bf16 v[30:33], v[156:159], v[224:227], v[30:33]
	v_mfma_f32_16x16x32_bf16 v[26:29], v[166:169], v[224:227], v[26:29]
	v_mfma_f32_16x16x32_bf16 v[14:17], v[156:159], v[232:235], v[14:17]
	v_mfma_f32_16x16x32_bf16 v[10:13], v[166:169], v[232:235], v[10:13]
	v_mfma_f32_16x16x32_bf16 v[62:65], v[162:165], v[212:215], v[62:65]
	v_mfma_f32_16x16x32_bf16 v[58:61], v[170:173], v[212:215], v[58:61]
	v_mfma_f32_16x16x32_bf16 v[46:49], v[162:165], v[220:223], v[46:49]
	v_mfma_f32_16x16x32_bf16 v[42:45], v[170:173], v[220:223], v[42:45]
	v_mfma_f32_16x16x32_bf16 v[30:33], v[162:165], v[228:231], v[30:33]
	v_mfma_f32_16x16x32_bf16 v[26:29], v[170:173], v[228:231], v[26:29]
	v_mfma_f32_16x16x32_bf16 v[14:17], v[162:165], v[236:239], v[14:17]
	v_mfma_f32_16x16x32_bf16 v[10:13], v[170:173], v[236:239], v[10:13]
	v_mfma_f32_16x16x32_bf16 v[54:57], v[174:177], v[208:211], v[54:57]
	v_mfma_f32_16x16x32_bf16 v[50:53], v[182:185], v[208:211], v[50:53]
	v_mfma_f32_16x16x32_bf16 v[38:41], v[174:177], v[216:219], v[38:41]
	v_mfma_f32_16x16x32_bf16 v[34:37], v[182:185], v[216:219], v[34:37]
	v_mfma_f32_16x16x32_bf16 v[22:25], v[174:177], v[224:227], v[22:25]
	v_mfma_f32_16x16x32_bf16 v[18:21], v[182:185], v[224:227], v[18:21]
	v_mfma_f32_16x16x32_bf16 v[6:9], v[174:177], v[232:235], v[6:9]
	v_mfma_f32_16x16x32_bf16 v[2:5], v[182:185], v[232:235], v[2:5]
	v_mfma_f32_16x16x32_bf16 v[54:57], v[178:181], v[212:215], v[54:57]
	v_mfma_f32_16x16x32_bf16 v[50:53], v[204:207], v[212:215], v[50:53]
	v_mfma_f32_16x16x32_bf16 v[38:41], v[178:181], v[220:223], v[38:41]
	v_mfma_f32_16x16x32_bf16 v[34:37], v[204:207], v[220:223], v[34:37]
	v_mfma_f32_16x16x32_bf16 v[22:25], v[178:181], v[228:231], v[22:25]
	v_mfma_f32_16x16x32_bf16 v[18:21], v[204:207], v[228:231], v[18:21]
	v_mfma_f32_16x16x32_bf16 v[6:9], v[178:181], v[236:239], v[6:9]
	v_mfma_f32_16x16x32_bf16 v[2:5], v[204:207], v[236:239], v[2:5]
	s_setprio 0
	s_barrier
	s_add_i32 s47, 0, 0x18000
	s_add_i32 s76, 0, 0x1c000
	v_add_u32_e32 v170, s47, v143
	v_add_u32_e32 v203, s76, v143
	ds_read_b128 v[156:159], v170
	ds_read_b128 v[162:165], v170 offset:1024
	ds_read_b128 v[166:169], v170 offset:2048
	ds_read_b128 v[170:173], v170 offset:3072
	ds_read_b128 v[174:177], v203
	ds_read_b128 v[178:181], v203 offset:1024
	ds_read_b128 v[182:185], v203 offset:2048
	ds_read_b128 v[204:207], v203 offset:3072
	s_add_u32 s58, s58, 0x80000
	s_addc_u32 s59, s59, 0
	s_mov_b32 m0, s34
	v_lshl_add_u64 v[246:247], s[58:59], 0, v[150:151]
	ds_read_b128 v[208:211], v161 offset:32768
	ds_read_b128 v[212:215], v161 offset:33792
	ds_read_b128 v[216:219], v161 offset:34816
	ds_read_b128 v[220:223], v161 offset:35840
	ds_read_b128 v[224:227], v161 offset:36864
	ds_read_b128 v[228:231], v161 offset:37888
	ds_read_b128 v[232:235], v161 offset:38912
	ds_read_b128 v[236:239], v161 offset:39936
	global_load_lds_dwordx4 v[246:247], off
	v_lshl_add_u64 v[246:247], s[58:59], 0, v[146:147]
	s_mov_b32 m0, s57
	s_nop 0
	global_load_lds_dwordx4 v[246:247], off
	s_waitcnt vmcnt(8)
	s_waitcnt lgkmcnt(0)
	s_setprio 1
	s_barrier
	v_mfma_f32_16x16x32_bf16 v[126:129], v[156:159], v[208:211], v[126:129]
	v_mfma_f32_16x16x32_bf16 v[122:125], v[166:169], v[208:211], v[122:125]
	v_mfma_f32_16x16x32_bf16 v[110:113], v[156:159], v[216:219], v[110:113]
	v_mfma_f32_16x16x32_bf16 v[106:109], v[166:169], v[216:219], v[106:109]
	v_mfma_f32_16x16x32_bf16 v[94:97], v[156:159], v[224:227], v[94:97]
	v_mfma_f32_16x16x32_bf16 v[90:93], v[166:169], v[224:227], v[90:93]
	v_mfma_f32_16x16x32_bf16 v[78:81], v[156:159], v[232:235], v[78:81]
	v_mfma_f32_16x16x32_bf16 v[74:77], v[166:169], v[232:235], v[74:77]
	v_mfma_f32_16x16x32_bf16 v[126:129], v[162:165], v[212:215], v[126:129]
	v_mfma_f32_16x16x32_bf16 v[122:125], v[170:173], v[212:215], v[122:125]
	v_mfma_f32_16x16x32_bf16 v[110:113], v[162:165], v[220:223], v[110:113]
	v_mfma_f32_16x16x32_bf16 v[106:109], v[170:173], v[220:223], v[106:109]
	v_mfma_f32_16x16x32_bf16 v[94:97], v[162:165], v[228:231], v[94:97]
	v_mfma_f32_16x16x32_bf16 v[90:93], v[170:173], v[228:231], v[90:93]
	v_mfma_f32_16x16x32_bf16 v[78:81], v[162:165], v[236:239], v[78:81]
	v_mfma_f32_16x16x32_bf16 v[74:77], v[170:173], v[236:239], v[74:77]
	v_mfma_f32_16x16x32_bf16 v[118:121], v[174:177], v[208:211], v[118:121]
	v_mfma_f32_16x16x32_bf16 v[114:117], v[182:185], v[208:211], v[114:117]
	v_mfma_f32_16x16x32_bf16 v[102:105], v[174:177], v[216:219], v[102:105]
	v_mfma_f32_16x16x32_bf16 v[98:101], v[182:185], v[216:219], v[98:101]
	v_mfma_f32_16x16x32_bf16 v[86:89], v[174:177], v[224:227], v[86:89]
	v_mfma_f32_16x16x32_bf16 v[82:85], v[182:185], v[224:227], v[82:85]
	v_mfma_f32_16x16x32_bf16 v[70:73], v[174:177], v[232:235], v[70:73]
	v_mfma_f32_16x16x32_bf16 v[66:69], v[182:185], v[232:235], v[66:69]
	v_mfma_f32_16x16x32_bf16 v[118:121], v[178:181], v[212:215], v[118:121]
	v_mfma_f32_16x16x32_bf16 v[114:117], v[204:207], v[212:215], v[114:117]
	v_mfma_f32_16x16x32_bf16 v[102:105], v[178:181], v[220:223], v[102:105]
	v_mfma_f32_16x16x32_bf16 v[98:101], v[204:207], v[220:223], v[98:101]
	v_mfma_f32_16x16x32_bf16 v[86:89], v[178:181], v[228:231], v[86:89]
	v_mfma_f32_16x16x32_bf16 v[82:85], v[204:207], v[228:231], v[82:85]
	v_mfma_f32_16x16x32_bf16 v[70:73], v[178:181], v[236:239], v[70:73]
	v_mfma_f32_16x16x32_bf16 v[66:69], v[204:207], v[236:239], v[66:69]
	s_setprio 0
	s_barrier
; #define PG8_STAGE(bufoff, gbase, voff) do { _Pragma("unroll") for (int _i = 0; _i < 2; ++_i) \
;         __builtin_amdgcn_global_load_lds((const unsigned*)((const char*)(gbase) + (voff)[_i]), (PG8_LAS unsigned*)(lds + (bufoff) + ldsw + _i * 8192), 16, 0, 0); } while (0)
; #define PG8_LDA(dst, b, h) do { _Pragma("unroll") for (int m = 0; m < 4; ++m) _Pragma("unroll") for (int k = 0; k < 2; ++k) dst[m][k] = *(const PG8_LAS bf16x8*)(lds + PG8_SA(b, h) + aoff + m * 2048 + k * 1024); } while (0)
; #define PG8_MMA(ai, bj, At, Bt) do { __builtin_amdgcn_s_setprio(1); _Pragma("unroll") for (int m = 0; m < 4; ++m) _Pragma("unroll") for (int n = 0; n < 2; ++n) _Pragma("unroll") for (int k = 0; k < 2; ++k) \
;         acc[ai][bj][m][n] = __builtin_amdgcn_mfma_f32_16x16x32_bf16(Bt[n][k], At[m][k], acc[ai][bj][m][n], 0, 0, 0); __builtin_amdgcn_s_setprio(0); } while (0)
; #define PG8_WAIT_V(n) asm volatile("s_waitcnt vmcnt(" #n ")" ::: "memory")
; #define PG8_WAIT_L(n) asm volatile("s_waitcnt lgkmcnt(" #n ")" ::: "memory")
; #define PG8_BAR __builtin_amdgcn_s_barrier()
; #define PG8_SCHED __builtin_amdgcn_sched_barrier(0)
;     __device__ __forceinline__ void operator()(const f32x4 (&acc)[2][2][4][2], const Unit& u, int wr, int wc, int fr, int fq) const {
;     ...
;             for (int m = 0; m < 4; ++m) { const size_t row = (size_t)(row0 + ai * HALF + m * 16); float ss = 0.f;
; #pragma unroll
;                 for (int bj = 0; bj < 2; ++bj) { const size_t off = row * DM + col0 + bj * HALF;
;                     f32x4 v0 = acc[ai][bj][m][0] + *(const f32x4*)(base + off), v1 = acc[ai][bj][m][1] + *(const f32x4*)(base + off + 4);
; template <class Epi, class Sched, bool ALIGN_EPI = false, bool SP2 = false>
; __device__ __forceinline__ void gemm_phase(PG8_LAS unsigned char* lds, const Gemm g, const Sched& S, const Epi& E) {
;     ...
;             PG8_LDA(At, 1, 1); PG8_STAGE(PG8_SB(1, 0), b3, voffB); PG8_STAGE(PG8_SB(1, 1), b3 + hstep, voffB); PG8_STAGE(PG8_SA(1, 0), a3, voffA);
;             PG8_WAIT_V(8); PG8_WAIT_L(0); PG8_BAR; PG8_MMA(1, 0, At, B0); PG8_MMA(1, 1, At, B1); PG8_BAR; PG8_SCHED;
	s_add_i32 s47, s47, s4
	v_lshl_add_u64 v[186:187], v[186:187], 0, s[68:69]
	s_mov_b32 m0, s47
	ds_read_b128 v[208:211], v161 offset:49152
	ds_read_b128 v[212:215], v161 offset:50176
	ds_read_b128 v[216:219], v161 offset:51200
	ds_read_b128 v[220:223], v161 offset:52224
	ds_read_b128 v[224:227], v161 offset:53248
	ds_read_b128 v[228:231], v161 offset:54272
	ds_read_b128 v[232:235], v161 offset:55296
	ds_read_b128 v[236:239], v161 offset:56320
	global_load_lds_dwordx4 v[186:187], off
	s_add_i32 m0, s47, 0x2000
	s_add_u32 s40, s40, 0x80080
	v_lshl_add_u64 v[186:187], v[240:241], 0, s[68:69]
	s_addc_u32 s41, s41, 0
	s_add_i32 s47, s76, s4
	global_load_lds_dwordx4 v[186:187], off
	v_lshl_add_u64 v[186:187], s[40:41], 0, v[148:149]
	s_mov_b32 m0, s47
	s_nop 0
	global_load_lds_dwordx4 v[186:187], off
	v_lshl_add_u64 v[186:187], s[40:41], 0, v[144:145]
	s_add_i32 m0, s47, 0x2000
	s_nop 0
	global_load_lds_dwordx4 v[186:187], off
	v_lshl_add_u64 v[186:187], v[242:243], 0, s[68:69]
	s_mov_b32 m0, s67
	s_nop 0
	global_load_lds_dwordx4 v[186:187], off
	v_lshl_add_u64 v[186:187], v[244:245], 0, s[68:69]
	s_mov_b32 m0, s28
	s_nop 0
	global_load_lds_dwordx4 v[186:187], off
	s_nop 0
	s_waitcnt vmcnt(8)
	s_waitcnt lgkmcnt(0)
	s_setprio 1
	s_barrier
	v_mfma_f32_16x16x32_bf16 v[62:65], v[156:159], v[208:211], v[62:65]
	v_mfma_f32_16x16x32_bf16 v[58:61], v[166:169], v[208:211], v[58:61]
	v_mfma_f32_16x16x32_bf16 v[46:49], v[156:159], v[216:219], v[46:49]
	v_mfma_f32_16x16x32_bf16 v[42:45], v[166:169], v[216:219], v[42:45]
	v_mfma_f32_16x16x32_bf16 v[30:33], v[156:159], v[224:227], v[30:33]
	v_mfma_f32_16x16x32_bf16 v[26:29], v[166:169], v[224:227], v[26:29]
	v_mfma_f32_16x16x32_bf16 v[14:17], v[156:159], v[232:235], v[14:17]
	v_mfma_f32_16x16x32_bf16 v[10:13], v[166:169], v[232:235], v[10:13]
	v_mfma_f32_16x16x32_bf16 v[62:65], v[162:165], v[212:215], v[62:65]
	v_mfma_f32_16x16x32_bf16 v[58:61], v[170:173], v[212:215], v[58:61]
	v_mfma_f32_16x16x32_bf16 v[46:49], v[162:165], v[220:223], v[46:49]
	v_mfma_f32_16x16x32_bf16 v[42:45], v[170:173], v[220:223], v[42:45]
	v_mfma_f32_16x16x32_bf16 v[30:33], v[162:165], v[228:231], v[30:33]
	v_mfma_f32_16x16x32_bf16 v[26:29], v[170:173], v[228:231], v[26:29]
	v_mfma_f32_16x16x32_bf16 v[14:17], v[162:165], v[236:239], v[14:17]
	v_mfma_f32_16x16x32_bf16 v[10:13], v[170:173], v[236:239], v[10:13]
	v_mfma_f32_16x16x32_bf16 v[54:57], v[174:177], v[208:211], v[54:57]
	v_mfma_f32_16x16x32_bf16 v[50:53], v[182:185], v[208:211], v[50:53]
	v_mfma_f32_16x16x32_bf16 v[38:41], v[174:177], v[216:219], v[38:41]
	v_mfma_f32_16x16x32_bf16 v[34:37], v[182:185], v[216:219], v[34:37]
	v_mfma_f32_16x16x32_bf16 v[22:25], v[174:177], v[224:227], v[22:25]
	v_mfma_f32_16x16x32_bf16 v[18:21], v[182:185], v[224:227], v[18:21]
	v_mfma_f32_16x16x32_bf16 v[6:9], v[174:177], v[232:235], v[6:9]
	v_mfma_f32_16x16x32_bf16 v[2:5], v[182:185], v[232:235], v[2:5]
	v_mfma_f32_16x16x32_bf16 v[54:57], v[178:181], v[212:215], v[54:57]
	v_mfma_f32_16x16x32_bf16 v[50:53], v[204:207], v[212:215], v[50:53]
	v_mfma_f32_16x16x32_bf16 v[38:41], v[178:181], v[220:223], v[38:41]
	v_mfma_f32_16x16x32_bf16 v[34:37], v[204:207], v[220:223], v[34:37]
	v_mfma_f32_16x16x32_bf16 v[22:25], v[178:181], v[228:231], v[22:25]
	v_mfma_f32_16x16x32_bf16 v[18:21], v[204:207], v[228:231], v[18:21]
	v_mfma_f32_16x16x32_bf16 v[6:9], v[178:181], v[236:239], v[6:9]
	v_mfma_f32_16x16x32_bf16 v[2:5], v[204:207], v[236:239], v[2:5]
	s_setprio 0
	s_barrier
	s_add_i32 s46, s46, 2
	s_add_u32 vcc_lo, vcc_lo, 0x100
	s_addc_u32 vcc_hi, vcc_hi, 0
	s_add_u32 s78, s78, 0x100
	s_addc_u32 s79, s79, 0
	s_cmp_gt_u32 s46, 29
	s_cbranch_scc0 .LBB0_98
	v_lshl_add_u32 v156, s73, 8, v1
	v_lshl_or_b32 v157, s54, 8, v160
	v_lshl_add_u32 v157, v156, 11, v157
	v_mov_b32_e32 v247, 0
	v_lshlrev_b32_e32 v246, 2, v157
	v_lshl_add_u64 v[162:163], s[8:9], 0, v[246:247]
	v_lshlrev_b32_e32 v246, 1, v157
	v_lshl_add_u64 v[244:245], s[70:71], 0, v[246:247]
	s_mov_b32 s41, 0
	global_load_dwordx4 v[164:167], v[162:163], off
	global_load_dwordx4 v[168:171], v[162:163], off offset:16
	global_load_dwordx4 v[172:175], v[162:163], off offset:512
	global_load_dwordx4 v[176:179], v[162:163], off offset:528
	s_mov_b32 s40, 0x20000
	v_lshl_add_u64 v[246:247], v[162:163], 0, s[40:41]
	global_load_dwordx4 v[180:183], v[246:247], off
	global_load_dwordx4 v[184:187], v[246:247], off offset:16
	global_load_dwordx4 v[204:207], v[246:247], off offset:512
	global_load_dwordx4 v[208:211], v[246:247], off offset:528
	s_mov_b32 s40, 0x40000
	v_lshl_add_u64 v[246:247], v[162:163], 0, s[40:41]
	global_load_dwordx4 v[212:215], v[246:247], off
	global_load_dwordx4 v[216:219], v[246:247], off offset:16
	global_load_dwordx4 v[220:223], v[246:247], off offset:512
	global_load_dwordx4 v[224:227], v[246:247], off offset:528
	s_mov_b32 s40, 0x60000
	v_lshl_add_u64 v[246:247], v[162:163], 0, s[40:41]
	global_load_dwordx4 v[228:231], v[246:247], off
	global_load_dwordx4 v[232:235], v[246:247], off offset:16
	global_load_dwordx4 v[236:239], v[246:247], off offset:512
	global_load_dwordx4 v[240:243], v[246:247], off offset:528
	s_and_b64 vcc, exec, s[36:37]
	s_cbranch_vccz .Lx1_nobar
	s_barrier

; #define PG8_STAGE(bufoff, gbase, voff) do { _Pragma("unroll") for (int _i = 0; _i < 2; ++_i) \
;         __builtin_amdgcn_global_load_lds((const unsigned*)((const char*)(gbase) + (voff)[_i]), (PG8_LAS unsigned*)(lds + (bufoff) + ldsw + _i * 8192), 16, 0, 0); } while (0)
; #define PG8_LDA(dst, b, h) do { _Pragma("unroll") for (int m = 0; m < 4; ++m) _Pragma("unroll") for (int k = 0; k < 2; ++k) dst[m][k] = *(const PG8_LAS bf16x8*)(lds + PG8_SA(b, h) + aoff + m * 2048 + k * 1024); } while (0)
; #define PG8_LDB(dst, b, h) do { _Pragma("unroll") for (int n = 0; n < 2; ++n) _Pragma("unroll") for (int k = 0; k < 2; ++k) dst[n][k] = *(const PG8_LAS bf16x8*)(lds + PG8_SB(b, h) + boff + n * 2048 + k * 1024); } while (0)
; #define PG8_MMA(ai, bj, At, Bt) do { __builtin_amdgcn_s_setprio(1); _Pragma("unroll") for (int m = 0; m < 4; ++m) _Pragma("unroll") for (int n = 0; n < 2; ++n) _Pragma("unroll") for (int k = 0; k < 2; ++k) \
;         acc[ai][bj][m][n] = __builtin_amdgcn_mfma_f32_16x16x32_bf16(Bt[n][k], At[m][k], acc[ai][bj][m][n], 0, 0, 0); __builtin_amdgcn_s_setprio(0); } while (0)
; #define PG8_WAIT_V(n) asm volatile("s_waitcnt vmcnt(" #n ")" ::: "memory")
; #define PG8_WAIT_L(n) asm volatile("s_waitcnt lgkmcnt(" #n ")" ::: "memory")
; #define PG8_BAR __builtin_amdgcn_s_barrier()
; #define PG8_SCHED __builtin_amdgcn_sched_barrier(0)
; template <class Epi, class Sched, bool ALIGN_EPI = false, bool SP2 = false>
; __device__ __forceinline__ void gemm_phase(PG8_LAS unsigned char* lds, const Gemm g, const Sched& S, const Epi& E) {
;     ...
;             const bool last = (t == nt - 2);
;             const char* a1 = cA + (size_t)(t + 1) * kstep;
;             const char* a2 = last ? nA : cA + (size_t)(t + 2) * kstep; const char* b2 = last ? nB : cB + (size_t)(t + 2) * kstep;
;             const char* a3 = a2 + kstep; const char* b3 = b2 + kstep;
;             if (last && has_next) S.a_ready(nxt);
;             if constexpr (SP2) {
;             PG8_LDB(B0, 0, 0); PG8_LDB(B1, 0, 1); PG8_SCHED; PG8_LDA(At, 0, 0); PG8_STAGE(PG8_SA(1, 1), a1 + hstep, voffA);
;             PG8_WAIT_V(8); PG8_WAIT_L(0); PG8_BAR; PG8_MMA(0, 0, At, B0); PG8_MMA(0, 1, At, B1); PG8_BAR; PG8_SCHED;
;             PG8_LDA(At, 0, 1); PG8_STAGE(PG8_SB(0, 0), b2, voffB); PG8_STAGE(PG8_SB(0, 1), b2 + hstep, voffB); PG8_STAGE(PG8_SA(0, 0), a2, voffA);
.LBB0_136:
	s_add_u32 s18, s58, 0xfffe0080
	s_addc_u32 s19, s59, -1
	s_add_i32 s46, 0, 0x10000
	s_cmp_eq_u32 s79, 4
	s_cselect_b32 s63, s37, s19
	s_cselect_b32 s62, s73, s18
	s_cselect_b32 s19, s11, s78
	s_cselect_b32 s18, s84, s85
	s_add_i32 s76, 0, 0x14000
	v_add_u32_e32 v172, s46, v1
	v_add_u32_e32 v203, s76, v1
	ds_read_b128 v[160:163], v172
	ds_read_b128 v[164:167], v172 offset:1024
	ds_read_b128 v[168:171], v172 offset:2048
	ds_read_b128 v[172:175], v172 offset:3072
	ds_read_b128 v[176:179], v203
	ds_read_b128 v[180:183], v203 offset:1024
	ds_read_b128 v[184:187], v203 offset:2048
	ds_read_b128 v[204:207], v203 offset:3072
	v_lshl_add_u64 v[240:241], s[58:59], 0, v[156:157]
	s_add_i32 m0, s5, 0xc000
	ds_read_b128 v[208:211], v143
	ds_read_b128 v[212:215], v143 offset:1024
	ds_read_b128 v[216:219], v143 offset:2048
	ds_read_b128 v[220:223], v143 offset:3072
	ds_read_b128 v[224:227], v143 offset:4096
	ds_read_b128 v[228:231], v143 offset:5120
	ds_read_b128 v[232:235], v143 offset:6144
	ds_read_b128 v[236:239], v143 offset:7168
	global_load_lds_dwordx4 v[240:241], off
	v_lshl_add_u64 v[240:241], s[58:59], 0, v[158:159]
	s_add_i32 m0, s5, 0xe000
	s_nop 0
	global_load_lds_dwordx4 v[240:241], off
	s_nop 0
	s_waitcnt vmcnt(8)
	s_waitcnt lgkmcnt(0)
	s_setprio 1
	s_barrier
	v_mfma_f32_16x16x32_bf16 v[126:129], v[160:163], v[208:211], v[126:129]
	v_mfma_f32_16x16x32_bf16 v[122:125], v[168:171], v[208:211], v[122:125]
	v_mfma_f32_16x16x32_bf16 v[110:113], v[160:163], v[216:219], v[110:113]
	v_mfma_f32_16x16x32_bf16 v[106:109], v[168:171], v[216:219], v[106:109]
	v_mfma_f32_16x16x32_bf16 v[94:97], v[160:163], v[224:227], v[94:97]
	v_mfma_f32_16x16x32_bf16 v[90:93], v[168:171], v[224:227], v[90:93]
	v_mfma_f32_16x16x32_bf16 v[78:81], v[160:163], v[232:235], v[78:81]
	v_mfma_f32_16x16x32_bf16 v[74:77], v[168:171], v[232:235], v[74:77]
	v_mfma_f32_16x16x32_bf16 v[126:129], v[164:167], v[212:215], v[126:129]
	v_mfma_f32_16x16x32_bf16 v[122:125], v[172:175], v[212:215], v[122:125]
	v_mfma_f32_16x16x32_bf16 v[110:113], v[164:167], v[220:223], v[110:113]
	v_mfma_f32_16x16x32_bf16 v[106:109], v[172:175], v[220:223], v[106:109]
	v_mfma_f32_16x16x32_bf16 v[94:97], v[164:167], v[228:231], v[94:97]
	v_mfma_f32_16x16x32_bf16 v[90:93], v[172:175], v[228:231], v[90:93]
	v_mfma_f32_16x16x32_bf16 v[78:81], v[164:167], v[236:239], v[78:81]
	v_mfma_f32_16x16x32_bf16 v[74:77], v[172:175], v[236:239], v[74:77]
	v_mfma_f32_16x16x32_bf16 v[118:121], v[176:179], v[208:211], v[118:121]
	v_mfma_f32_16x16x32_bf16 v[114:117], v[184:187], v[208:211], v[114:117]
	v_mfma_f32_16x16x32_bf16 v[102:105], v[176:179], v[216:219], v[102:105]
	v_mfma_f32_16x16x32_bf16 v[98:101], v[184:187], v[216:219], v[98:101]
	v_mfma_f32_16x16x32_bf16 v[86:89], v[176:179], v[224:227], v[86:89]
	v_mfma_f32_16x16x32_bf16 v[82:85], v[184:187], v[224:227], v[82:85]
	v_mfma_f32_16x16x32_bf16 v[70:73], v[176:179], v[232:235], v[70:73]
	v_mfma_f32_16x16x32_bf16 v[66:69], v[184:187], v[232:235], v[66:69]
	v_mfma_f32_16x16x32_bf16 v[118:121], v[180:183], v[212:215], v[118:121]
	v_mfma_f32_16x16x32_bf16 v[114:117], v[204:207], v[212:215], v[114:117]
	v_mfma_f32_16x16x32_bf16 v[102:105], v[180:183], v[220:223], v[102:105]
	v_mfma_f32_16x16x32_bf16 v[98:101], v[204:207], v[220:223], v[98:101]
	v_mfma_f32_16x16x32_bf16 v[86:89], v[180:183], v[228:231], v[86:89]
	v_mfma_f32_16x16x32_bf16 v[82:85], v[204:207], v[228:231], v[82:85]
	v_mfma_f32_16x16x32_bf16 v[70:73], v[180:183], v[236:239], v[70:73]
	v_mfma_f32_16x16x32_bf16 v[66:69], v[204:207], v[236:239], v[66:69]
	s_setprio 0
	s_barrier
	s_add_i32 s46, s46, s4
	v_lshl_add_u64 v[240:241], s[18:19], 0, v[148:149]
	s_mov_b32 m0, s46
	ds_read_b128 v[208:211], v143 offset:16384
	ds_read_b128 v[212:215], v143 offset:17408
	ds_read_b128 v[216:219], v143 offset:18432
	ds_read_b128 v[220:223], v143 offset:19456
	ds_read_b128 v[224:227], v143 offset:20480
	ds_read_b128 v[228:231], v143 offset:21504
	ds_read_b128 v[232:235], v143 offset:22528
	ds_read_b128 v[236:239], v143 offset:23552
	global_load_lds_dwordx4 v[240:241], off
	s_add_i32 m0, s46, 0x2000
	s_add_u32 s46, s18, 0x20000
	v_lshl_add_u64 v[242:243], s[18:19], 0, v[144:145]
	s_addc_u32 s47, s19, 0
	s_add_i32 s76, s76, s4
	global_load_lds_dwordx4 v[242:243], off
	v_lshl_add_u64 v[244:245], s[46:47], 0, v[148:149]
	s_mov_b32 m0, s76
	v_lshl_add_u64 v[246:247], s[62:63], 0, v[146:147]
	global_load_lds_dwordx4 v[244:245], off
	v_lshl_add_u64 v[244:245], s[46:47], 0, v[144:145]
	s_add_i32 m0, s76, 0x2000
	s_nop 0
	global_load_lds_dwordx4 v[244:245], off
	v_lshl_add_u64 v[244:245], s[62:63], 0, v[150:151]
	s_mov_b32 m0, s5
	s_nop 0
	global_load_lds_dwordx4 v[244:245], off
	s_mov_b32 m0, s28
	s_nop 0
	global_load_lds_dwordx4 v[246:247], off
	s_waitcnt vmcnt(8)
	s_waitcnt lgkmcnt(0)
	s_setprio 1
	s_barrier
; #define PG8_STAGE(bufoff, gbase, voff) do { _Pragma("unroll") for (int _i = 0; _i < 2; ++_i) \
;         __builtin_amdgcn_global_load_lds((const unsigned*)((const char*)(gbase) + (voff)[_i]), (PG8_LAS unsigned*)(lds + (bufoff) + ldsw + _i * 8192), 16, 0, 0); } while (0)
; #define PG8_LDA(dst, b, h) do { _Pragma("unroll") for (int m = 0; m < 4; ++m) _Pragma("unroll") for (int k = 0; k < 2; ++k) dst[m][k] = *(const PG8_LAS bf16x8*)(lds + PG8_SA(b, h) + aoff + m * 2048 + k * 1024); } while (0)
; #define PG8_LDB(dst, b, h) do { _Pragma("unroll") for (int n = 0; n < 2; ++n) _Pragma("unroll") for (int k = 0; k < 2; ++k) dst[n][k] = *(const PG8_LAS bf16x8*)(lds + PG8_SB(b, h) + boff + n * 2048 + k * 1024); } while (0)
; #define PG8_MMA(ai, bj, At, Bt) do { __builtin_amdgcn_s_setprio(1); _Pragma("unroll") for (int m = 0; m < 4; ++m) _Pragma("unroll") for (int n = 0; n < 2; ++n) _Pragma("unroll") for (int k = 0; k < 2; ++k) \
;         acc[ai][bj][m][n] = __builtin_amdgcn_mfma_f32_16x16x32_bf16(Bt[n][k], At[m][k], acc[ai][bj][m][n], 0, 0, 0); __builtin_amdgcn_s_setprio(0); } while (0)
; #define PG8_WAIT_V(n) asm volatile("s_waitcnt vmcnt(" #n ")" ::: "memory")
; #define PG8_WAIT_L(n) asm volatile("s_waitcnt lgkmcnt(" #n ")" ::: "memory")
; #define PG8_BAR __builtin_amdgcn_s_barrier()
; #define PG8_SCHED __builtin_amdgcn_sched_barrier(0)
; template <class Epi, class Sched, bool ALIGN_EPI = false, bool SP2 = false>
; __device__ __forceinline__ void gemm_phase(PG8_LAS unsigned char* lds, const Gemm g, const Sched& S, const Epi& E) {
;     ...
;             PG8_WAIT_V(8); PG8_WAIT_L(0); PG8_BAR; PG8_MMA(1, 0, At, B0); PG8_MMA(1, 1, At, B1); PG8_BAR; PG8_SCHED;
;             PG8_LDB(B0, 1, 0); PG8_LDB(B1, 1, 1); PG8_SCHED; PG8_LDA(At, 1, 0); PG8_STAGE(PG8_SA(0, 1), a2 + hstep, voffA);
;             PG8_WAIT_V(8); PG8_WAIT_L(0); PG8_BAR; PG8_MMA(0, 0, At, B0); PG8_MMA(0, 1, At, B1); PG8_BAR; PG8_SCHED;
	v_mfma_f32_16x16x32_bf16 v[62:65], v[160:163], v[208:211], v[62:65]
	v_mfma_f32_16x16x32_bf16 v[58:61], v[168:171], v[208:211], v[58:61]
	v_mfma_f32_16x16x32_bf16 v[46:49], v[160:163], v[216:219], v[46:49]
	v_mfma_f32_16x16x32_bf16 v[42:45], v[168:171], v[216:219], v[42:45]
	v_mfma_f32_16x16x32_bf16 v[30:33], v[160:163], v[224:227], v[30:33]
	v_mfma_f32_16x16x32_bf16 v[26:29], v[168:171], v[224:227], v[26:29]
	v_mfma_f32_16x16x32_bf16 v[14:17], v[160:163], v[232:235], v[14:17]
	v_mfma_f32_16x16x32_bf16 v[10:13], v[168:171], v[232:235], v[10:13]
	v_mfma_f32_16x16x32_bf16 v[62:65], v[164:167], v[212:215], v[62:65]
	v_mfma_f32_16x16x32_bf16 v[58:61], v[172:175], v[212:215], v[58:61]
	v_mfma_f32_16x16x32_bf16 v[46:49], v[164:167], v[220:223], v[46:49]
	v_mfma_f32_16x16x32_bf16 v[42:45], v[172:175], v[220:223], v[42:45]
	v_mfma_f32_16x16x32_bf16 v[30:33], v[164:167], v[228:231], v[30:33]
	v_mfma_f32_16x16x32_bf16 v[26:29], v[172:175], v[228:231], v[26:29]
	v_mfma_f32_16x16x32_bf16 v[14:17], v[164:167], v[236:239], v[14:17]
	v_mfma_f32_16x16x32_bf16 v[10:13], v[172:175], v[236:239], v[10:13]
	v_mfma_f32_16x16x32_bf16 v[54:57], v[176:179], v[208:211], v[54:57]
	v_mfma_f32_16x16x32_bf16 v[50:53], v[184:187], v[208:211], v[50:53]
	v_mfma_f32_16x16x32_bf16 v[38:41], v[176:179], v[216:219], v[38:41]
	v_mfma_f32_16x16x32_bf16 v[34:37], v[184:187], v[216:219], v[34:37]
	v_mfma_f32_16x16x32_bf16 v[22:25], v[176:179], v[224:227], v[22:25]
	v_mfma_f32_16x16x32_bf16 v[18:21], v[184:187], v[224:227], v[18:21]
	v_mfma_f32_16x16x32_bf16 v[6:9], v[176:179], v[232:235], v[6:9]
	v_mfma_f32_16x16x32_bf16 v[2:5], v[184:187], v[232:235], v[2:5]
	v_mfma_f32_16x16x32_bf16 v[54:57], v[180:183], v[212:215], v[54:57]
	v_mfma_f32_16x16x32_bf16 v[50:53], v[204:207], v[212:215], v[50:53]
	v_mfma_f32_16x16x32_bf16 v[38:41], v[180:183], v[220:223], v[38:41]
	v_mfma_f32_16x16x32_bf16 v[34:37], v[204:207], v[220:223], v[34:37]
	v_mfma_f32_16x16x32_bf16 v[22:25], v[180:183], v[228:231], v[22:25]
	v_mfma_f32_16x16x32_bf16 v[18:21], v[204:207], v[228:231], v[18:21]
	v_mfma_f32_16x16x32_bf16 v[6:9], v[180:183], v[236:239], v[6:9]
	v_mfma_f32_16x16x32_bf16 v[2:5], v[204:207], v[236:239], v[2:5]
	s_setprio 0
	s_barrier
	s_add_i32 s76, 0, 0x18000
	s_add_i32 s77, 0, 0x1c000
	v_add_u32_e32 v172, s76, v1
	v_add_u32_e32 v203, s77, v1
	ds_read_b128 v[160:163], v172
	ds_read_b128 v[164:167], v172 offset:1024
	ds_read_b128 v[168:171], v172 offset:2048
	ds_read_b128 v[172:175], v172 offset:3072
	ds_read_b128 v[176:179], v203
	ds_read_b128 v[180:183], v203 offset:1024
	ds_read_b128 v[184:187], v203 offset:2048
	ds_read_b128 v[204:207], v203 offset:3072
	s_add_u32 s46, s62, 0x20000
	s_addc_u32 s47, s63, 0
	s_mov_b32 m0, s30
	v_lshl_add_u64 v[248:249], s[46:47], 0, v[150:151]
	ds_read_b128 v[208:211], v143 offset:32768
	ds_read_b128 v[212:215], v143 offset:33792
	ds_read_b128 v[216:219], v143 offset:34816
	ds_read_b128 v[220:223], v143 offset:35840
	ds_read_b128 v[224:227], v143 offset:36864
	ds_read_b128 v[228:231], v143 offset:37888
	ds_read_b128 v[232:235], v143 offset:38912
	ds_read_b128 v[236:239], v143 offset:39936
	global_load_lds_dwordx4 v[248:249], off
	v_lshl_add_u64 v[248:249], s[46:47], 0, v[146:147]
	s_mov_b32 m0, s34
	s_nop 0
	global_load_lds_dwordx4 v[248:249], off
	s_waitcnt vmcnt(8)
	s_waitcnt lgkmcnt(0)
	s_setprio 1
	s_barrier
	v_mfma_f32_16x16x32_bf16 v[126:129], v[160:163], v[208:211], v[126:129]
	v_mfma_f32_16x16x32_bf16 v[122:125], v[168:171], v[208:211], v[122:125]
	v_mfma_f32_16x16x32_bf16 v[110:113], v[160:163], v[216:219], v[110:113]
	v_mfma_f32_16x16x32_bf16 v[106:109], v[168:171], v[216:219], v[106:109]
	v_mfma_f32_16x16x32_bf16 v[94:97], v[160:163], v[224:227], v[94:97]
	v_mfma_f32_16x16x32_bf16 v[90:93], v[168:171], v[224:227], v[90:93]
	v_mfma_f32_16x16x32_bf16 v[78:81], v[160:163], v[232:235], v[78:81]
	v_mfma_f32_16x16x32_bf16 v[74:77], v[168:171], v[232:235], v[74:77]
	v_mfma_f32_16x16x32_bf16 v[126:129], v[164:167], v[212:215], v[126:129]
	v_mfma_f32_16x16x32_bf16 v[122:125], v[172:175], v[212:215], v[122:125]
	v_mfma_f32_16x16x32_bf16 v[110:113], v[164:167], v[220:223], v[110:113]
	v_mfma_f32_16x16x32_bf16 v[106:109], v[172:175], v[220:223], v[106:109]
	v_mfma_f32_16x16x32_bf16 v[94:97], v[164:167], v[228:231], v[94:97]
	v_mfma_f32_16x16x32_bf16 v[90:93], v[172:175], v[228:231], v[90:93]
	v_mfma_f32_16x16x32_bf16 v[78:81], v[164:167], v[236:239], v[78:81]
	v_mfma_f32_16x16x32_bf16 v[74:77], v[172:175], v[236:239], v[74:77]
	v_mfma_f32_16x16x32_bf16 v[118:121], v[176:179], v[208:211], v[118:121]
	v_mfma_f32_16x16x32_bf16 v[114:117], v[184:187], v[208:211], v[114:117]
	v_mfma_f32_16x16x32_bf16 v[102:105], v[176:179], v[216:219], v[102:105]
	v_mfma_f32_16x16x32_bf16 v[98:101], v[184:187], v[216:219], v[98:101]
	v_mfma_f32_16x16x32_bf16 v[86:89], v[176:179], v[224:227], v[86:89]
	v_mfma_f32_16x16x32_bf16 v[82:85], v[184:187], v[224:227], v[82:85]
	v_mfma_f32_16x16x32_bf16 v[70:73], v[176:179], v[232:235], v[70:73]
	v_mfma_f32_16x16x32_bf16 v[66:69], v[184:187], v[232:235], v[66:69]
	v_mfma_f32_16x16x32_bf16 v[118:121], v[180:183], v[212:215], v[118:121]
	v_mfma_f32_16x16x32_bf16 v[114:117], v[204:207], v[212:215], v[114:117]
	v_mfma_f32_16x16x32_bf16 v[102:105], v[180:183], v[220:223], v[102:105]
	v_mfma_f32_16x16x32_bf16 v[98:101], v[204:207], v[220:223], v[98:101]
	v_mfma_f32_16x16x32_bf16 v[86:89], v[180:183], v[228:231], v[86:89]
	v_mfma_f32_16x16x32_bf16 v[82:85], v[204:207], v[228:231], v[82:85]
	v_mfma_f32_16x16x32_bf16 v[70:73], v[180:183], v[236:239], v[70:73]
	v_mfma_f32_16x16x32_bf16 v[66:69], v[204:207], v[236:239], v[66:69]
	s_setprio 0
	s_barrier
; #define PG8_STAGE(bufoff, gbase, voff) do { _Pragma("unroll") for (int _i = 0; _i < 2; ++_i) \
;         __builtin_amdgcn_global_load_lds((const unsigned*)((const char*)(gbase) + (voff)[_i]), (PG8_LAS unsigned*)(lds + (bufoff) + ldsw + _i * 8192), 16, 0, 0); } while (0)
; #define PG8_LDA(dst, b, h) do { _Pragma("unroll") for (int m = 0; m < 4; ++m) _Pragma("unroll") for (int k = 0; k < 2; ++k) dst[m][k] = *(const PG8_LAS bf16x8*)(lds + PG8_SA(b, h) + aoff + m * 2048 + k * 1024); } while (0)
; #define PG8_MMA(ai, bj, At, Bt) do { __builtin_amdgcn_s_setprio(1); _Pragma("unroll") for (int m = 0; m < 4; ++m) _Pragma("unroll") for (int n = 0; n < 2; ++n) _Pragma("unroll") for (int k = 0; k < 2; ++k) \
;         acc[ai][bj][m][n] = __builtin_amdgcn_mfma_f32_16x16x32_bf16(Bt[n][k], At[m][k], acc[ai][bj][m][n], 0, 0, 0); __builtin_amdgcn_s_setprio(0); } while (0)
; #define PG8_WAIT_V(n) asm volatile("s_waitcnt vmcnt(" #n ")" ::: "memory")
; #define PG8_WAIT_L(n) asm volatile("s_waitcnt lgkmcnt(" #n ")" ::: "memory")
; #define PG8_BAR __builtin_amdgcn_s_barrier()
; #define PG8_SCHED __builtin_amdgcn_sched_barrier(0)
;     __device__ __forceinline__ void operator()(const f32x4 (&acc)[2][2][4][2], const Unit& u, int wr, int wc, int fr, int fq) const {
;     ...
;         const u32x4* gp = (const u32x4*)G8 + (size_t)(u.pm * 16 + gsel + u.pn) * 8 * 512 + tidn;
;         u32x4* mp = M1 + (size_t)(u.pm * 8 + u.pn) * 16 * 512 + tidn;
;         constexpr float K255 = 1.0f / 255.0f;
; #pragma unroll
;         for (int ai = 0; ai < 2; ++ai)
; #pragma unroll
;             for (int m = 0; m < 4; ++m) { const size_t row = (size_t)(row0 + ai * HALF + m * 16);
;                 const u32x4 gw = gp[(ai * 4 + m) * 512];
; template <class Epi, class Sched, bool ALIGN_EPI = false, bool SP2 = false>
; __device__ __forceinline__ void gemm_phase(PG8_LAS unsigned char* lds, const Gemm g, const Sched& S, const Epi& E) {
;     ...
;             PG8_LDA(At, 1, 1); PG8_STAGE(PG8_SB(1, 0), b3, voffB); PG8_STAGE(PG8_SB(1, 1), b3 + hstep, voffB); PG8_STAGE(PG8_SA(1, 0), a3, voffA);
;             PG8_WAIT_V(8); PG8_WAIT_L(0); PG8_BAR; PG8_MMA(1, 0, At, B0); PG8_MMA(1, 1, At, B1); PG8_BAR; PG8_SCHED;
	s_add_i32 s46, s76, s4
	v_lshl_add_u64 v[240:241], v[240:241], 0, s[68:69]
	s_mov_b32 m0, s46
	ds_read_b128 v[208:211], v143 offset:49152
	ds_read_b128 v[212:215], v143 offset:50176
	ds_read_b128 v[216:219], v143 offset:51200
	ds_read_b128 v[220:223], v143 offset:52224
	ds_read_b128 v[224:227], v143 offset:53248
	ds_read_b128 v[228:231], v143 offset:54272
	ds_read_b128 v[232:235], v143 offset:55296
	ds_read_b128 v[236:239], v143 offset:56320
	global_load_lds_dwordx4 v[240:241], off
	s_add_i32 m0, s46, 0x2000
	s_add_u32 s18, s18, 0x20080
	v_lshl_add_u64 v[240:241], v[242:243], 0, s[68:69]
	s_addc_u32 s19, s19, 0
	s_add_i32 s46, s77, s4
	global_load_lds_dwordx4 v[240:241], off
	v_lshl_add_u64 v[240:241], s[18:19], 0, v[148:149]
	s_mov_b32 m0, s46
	s_nop 0
	global_load_lds_dwordx4 v[240:241], off
	v_lshl_add_u64 v[240:241], s[18:19], 0, v[144:145]
	s_add_i32 m0, s46, 0x2000
	s_nop 0
	global_load_lds_dwordx4 v[240:241], off
	v_lshl_add_u64 v[240:241], v[244:245], 0, s[68:69]
	s_mov_b32 m0, s54
	s_nop 0
	global_load_lds_dwordx4 v[240:241], off
	v_lshl_add_u64 v[240:241], v[246:247], 0, s[68:69]
	s_mov_b32 m0, s57
	s_nop 0
	global_load_lds_dwordx4 v[240:241], off
	s_nop 0
	s_waitcnt vmcnt(8)
	s_waitcnt lgkmcnt(0)
	s_setprio 1
	s_barrier
	v_mfma_f32_16x16x32_bf16 v[62:65], v[160:163], v[208:211], v[62:65]
	v_mfma_f32_16x16x32_bf16 v[58:61], v[168:171], v[208:211], v[58:61]
	v_mfma_f32_16x16x32_bf16 v[46:49], v[160:163], v[216:219], v[46:49]
	v_mfma_f32_16x16x32_bf16 v[42:45], v[168:171], v[216:219], v[42:45]
	v_mfma_f32_16x16x32_bf16 v[30:33], v[160:163], v[224:227], v[30:33]
	v_mfma_f32_16x16x32_bf16 v[26:29], v[168:171], v[224:227], v[26:29]
	v_mfma_f32_16x16x32_bf16 v[14:17], v[160:163], v[232:235], v[14:17]
	v_mfma_f32_16x16x32_bf16 v[10:13], v[168:171], v[232:235], v[10:13]
	v_mfma_f32_16x16x32_bf16 v[62:65], v[164:167], v[212:215], v[62:65]
	v_mfma_f32_16x16x32_bf16 v[58:61], v[172:175], v[212:215], v[58:61]
	v_mfma_f32_16x16x32_bf16 v[46:49], v[164:167], v[220:223], v[46:49]
	v_mfma_f32_16x16x32_bf16 v[42:45], v[172:175], v[220:223], v[42:45]
	v_mfma_f32_16x16x32_bf16 v[30:33], v[164:167], v[228:231], v[30:33]
	v_mfma_f32_16x16x32_bf16 v[26:29], v[172:175], v[228:231], v[26:29]
	v_mfma_f32_16x16x32_bf16 v[14:17], v[164:167], v[236:239], v[14:17]
	v_mfma_f32_16x16x32_bf16 v[10:13], v[172:175], v[236:239], v[10:13]
	v_mfma_f32_16x16x32_bf16 v[54:57], v[176:179], v[208:211], v[54:57]
	v_mfma_f32_16x16x32_bf16 v[50:53], v[184:187], v[208:211], v[50:53]
	v_mfma_f32_16x16x32_bf16 v[38:41], v[176:179], v[216:219], v[38:41]
	v_mfma_f32_16x16x32_bf16 v[34:37], v[184:187], v[216:219], v[34:37]
	v_mfma_f32_16x16x32_bf16 v[22:25], v[176:179], v[224:227], v[22:25]
	v_mfma_f32_16x16x32_bf16 v[18:21], v[184:187], v[224:227], v[18:21]
	v_mfma_f32_16x16x32_bf16 v[6:9], v[176:179], v[232:235], v[6:9]
	v_mfma_f32_16x16x32_bf16 v[2:5], v[184:187], v[232:235], v[2:5]
	v_mfma_f32_16x16x32_bf16 v[54:57], v[180:183], v[212:215], v[54:57]
	v_mfma_f32_16x16x32_bf16 v[50:53], v[204:207], v[212:215], v[50:53]
	v_mfma_f32_16x16x32_bf16 v[38:41], v[180:183], v[220:223], v[38:41]
	v_mfma_f32_16x16x32_bf16 v[34:37], v[204:207], v[220:223], v[34:37]
	v_mfma_f32_16x16x32_bf16 v[22:25], v[180:183], v[228:231], v[22:25]
	v_mfma_f32_16x16x32_bf16 v[18:21], v[204:207], v[228:231], v[18:21]
	v_mfma_f32_16x16x32_bf16 v[6:9], v[180:183], v[236:239], v[6:9]
	v_mfma_f32_16x16x32_bf16 v[2:5], v[204:207], v[236:239], v[2:5]
	s_setprio 0
	s_barrier
	s_add_i32 s79, s79, 2
	s_add_u32 s58, s58, 0x100
	s_addc_u32 s59, s59, 0
	s_add_u32 s85, s85, 0x100
	s_addc_u32 s78, s78, 0
	s_cmp_gt_u32 s79, 5
	s_cbranch_scc0 .LBB0_136
	s_lshl_b32 s11, s67, 4
	s_add_i32 s18, s11, s86
	s_ashr_i32 s19, s18, 31
	s_lshl_b64 s[46:47], s[18:19], 16
	v_lshl_add_u64 v[162:163], v[152:153], 0, s[46:47]
	s_lshl_b32 s11, s67, 3
	s_sub_i32 s18, s18, s11
	s_ashr_i32 s19, s18, 31
	s_lshl_b64 s[18:19], s[18:19], 17
	v_lshl_add_u64 v[160:161], v[154:155], 0, s[18:19]
	s_mov_b32 s47, 0
	global_load_dwordx4 v[168:171], v[162:163], off
	s_mov_b32 s46, 0x2000
	v_lshl_add_u64 v[164:165], v[162:163], 0, s[46:47]
	global_load_dwordx4 v[172:175], v[164:165], off
	s_mov_b32 s46, 0x4000
	v_lshl_add_u64 v[164:165], v[162:163], 0, s[46:47]
	global_load_dwordx4 v[176:179], v[164:165], off
	s_mov_b32 s46, 0x6000
	v_lshl_add_u64 v[164:165], v[162:163], 0, s[46:47]
	global_load_dwordx4 v[180:183], v[164:165], off
	s_mov_b32 s46, 0x8000
	v_lshl_add_u64 v[164:165], v[162:163], 0, s[46:47]
	global_load_dwordx4 v[184:187], v[164:165], off
	s_mov_b32 s46, 0xa000
	v_lshl_add_u64 v[164:165], v[162:163], 0, s[46:47]
	global_load_dwordx4 v[204:207], v[164:165], off
	s_mov_b32 s46, 0xc000
	v_lshl_add_u64 v[164:165], v[162:163], 0, s[46:47]
	global_load_dwordx4 v[208:211], v[164:165], off
	s_mov_b32 s46, 0xe000
	v_lshl_add_u64 v[164:165], v[162:163], 0, s[46:47]
	global_load_dwordx4 v[212:215], v[164:165], off
	s_and_b64 vcc, exec, s[8:9]
	s_cbranch_vccz .Lg0_nobar
	s_barrier

; #define PG8_STAGE(bufoff, gbase, voff) do { _Pragma("unroll") for (int _i = 0; _i < 2; ++_i) \
;         __builtin_amdgcn_global_load_lds((const unsigned*)((const char*)(gbase) + (voff)[_i]), (PG8_LAS unsigned*)(lds + (bufoff) + ldsw + _i * 8192), 16, 0, 0); } while (0)
; #define PG8_LDA(dst, b, h) do { _Pragma("unroll") for (int m = 0; m < 4; ++m) _Pragma("unroll") for (int k = 0; k < 2; ++k) dst[m][k] = *(const PG8_LAS bf16x8*)(lds + PG8_SA(b, h) + aoff + m * 2048 + k * 1024); } while (0)
; #define PG8_LDB(dst, b, h) do { _Pragma("unroll") for (int n = 0; n < 2; ++n) _Pragma("unroll") for (int k = 0; k < 2; ++k) dst[n][k] = *(const PG8_LAS bf16x8*)(lds + PG8_SB(b, h) + boff + n * 2048 + k * 1024); } while (0)
; #define PG8_MMA(ai, bj, At, Bt) do { __builtin_amdgcn_s_setprio(1); _Pragma("unroll") for (int m = 0; m < 4; ++m) _Pragma("unroll") for (int n = 0; n < 2; ++n) _Pragma("unroll") for (int k = 0; k < 2; ++k) \
;         acc[ai][bj][m][n] = __builtin_amdgcn_mfma_f32_16x16x32_bf16(Bt[n][k], At[m][k], acc[ai][bj][m][n], 0, 0, 0); __builtin_amdgcn_s_setprio(0); } while (0)
; #define PG8_WAIT_V(n) asm volatile("s_waitcnt vmcnt(" #n ")" ::: "memory")
; #define PG8_WAIT_L(n) asm volatile("s_waitcnt lgkmcnt(" #n ")" ::: "memory")
; #define PG8_BAR __builtin_amdgcn_s_barrier()
; #define PG8_SCHED __builtin_amdgcn_sched_barrier(0)
; template <class Epi, class Sched, bool ALIGN_EPI = false, bool SP2 = false>
; __device__ __forceinline__ void gemm_phase(PG8_LAS unsigned char* lds, const Gemm g, const Sched& S, const Epi& E) {
;     ...
;             const bool last = (t == nt - 2);
;             const char* a1 = cA + (size_t)(t + 1) * kstep;
;             const char* a2 = last ? nA : cA + (size_t)(t + 2) * kstep; const char* b2 = last ? nB : cB + (size_t)(t + 2) * kstep;
;             const char* a3 = a2 + kstep; const char* b3 = b2 + kstep;
;             if (last && has_next) S.a_ready(nxt);
;             if constexpr (SP2) {
;             PG8_LDB(B0, 0, 0); PG8_LDB(B1, 0, 1); PG8_SCHED; PG8_LDA(At, 0, 0); PG8_STAGE(PG8_SA(1, 1), a1 + hstep, voffA);
;             PG8_WAIT_V(8); PG8_WAIT_L(0); PG8_BAR; PG8_MMA(0, 0, At, B0); PG8_MMA(0, 1, At, B1); PG8_BAR; PG8_SCHED;
;             PG8_LDA(At, 0, 1); PG8_STAGE(PG8_SB(0, 0), b2, voffB); PG8_STAGE(PG8_SB(0, 1), b2 + hstep, voffB); PG8_STAGE(PG8_SA(0, 0), a2, voffA);
.LBB0_160:
	s_add_u32 s42, s36, 0x100
	s_addc_u32 s43, s37, 0
	s_add_i32 s47, 0, 0x10000
	s_cmp_eq_u32 s46, 20
	s_cselect_b32 s45, s1, s43
	s_cselect_b32 s44, s0, s42
	s_cselect_b32 s19, s7, s73
	s_cselect_b32 s18, s6, s60
	s_add_i32 s76, 0, 0x14000
	v_add_u32_e32 v174, s47, v143
	v_add_u32_e32 v186, s76, v143
	ds_read_b128 v[160:163], v174
	ds_read_b128 v[164:167], v174 offset:1024
	ds_read_b128 v[170:173], v174 offset:2048
	ds_read_b128 v[174:177], v174 offset:3072
	ds_read_b128 v[178:181], v186
	ds_read_b128 v[182:185], v186 offset:1024
	ds_read_b128 v[204:207], v186 offset:2048
	ds_read_b128 v[208:211], v186 offset:3072
	v_lshl_add_u64 v[186:187], s[36:37], 0, v[156:157]
	s_add_i32 m0, s54, 0xc000
	ds_read_b128 v[212:215], v169
	ds_read_b128 v[216:219], v169 offset:1024
	ds_read_b128 v[220:223], v169 offset:2048
	ds_read_b128 v[224:227], v169 offset:3072
	ds_read_b128 v[228:231], v169 offset:4096
	ds_read_b128 v[232:235], v169 offset:5120
	ds_read_b128 v[236:239], v169 offset:6144
	ds_read_b128 v[240:243], v169 offset:7168
	global_load_lds_dwordx4 v[186:187], off
	v_lshl_add_u64 v[186:187], s[36:37], 0, v[158:159]
	s_add_i32 m0, s54, 0xe000
	s_nop 0
	global_load_lds_dwordx4 v[186:187], off
	s_waitcnt vmcnt(8)
	s_waitcnt lgkmcnt(0)
	s_setprio 1
	s_barrier
	v_mfma_f32_16x16x32_bf16 v[126:129], v[160:163], v[212:215], v[126:129]
	v_mfma_f32_16x16x32_bf16 v[122:125], v[170:173], v[212:215], v[122:125]
	v_mfma_f32_16x16x32_bf16 v[110:113], v[160:163], v[220:223], v[110:113]
	v_mfma_f32_16x16x32_bf16 v[106:109], v[170:173], v[220:223], v[106:109]
	v_mfma_f32_16x16x32_bf16 v[94:97], v[160:163], v[228:231], v[94:97]
	v_mfma_f32_16x16x32_bf16 v[90:93], v[170:173], v[228:231], v[90:93]
	v_mfma_f32_16x16x32_bf16 v[78:81], v[160:163], v[236:239], v[78:81]
	v_mfma_f32_16x16x32_bf16 v[74:77], v[170:173], v[236:239], v[74:77]
	v_mfma_f32_16x16x32_bf16 v[126:129], v[164:167], v[216:219], v[126:129]
	v_mfma_f32_16x16x32_bf16 v[122:125], v[174:177], v[216:219], v[122:125]
	v_mfma_f32_16x16x32_bf16 v[110:113], v[164:167], v[224:227], v[110:113]
	v_mfma_f32_16x16x32_bf16 v[106:109], v[174:177], v[224:227], v[106:109]
	v_mfma_f32_16x16x32_bf16 v[94:97], v[164:167], v[232:235], v[94:97]
	v_mfma_f32_16x16x32_bf16 v[90:93], v[174:177], v[232:235], v[90:93]
	v_mfma_f32_16x16x32_bf16 v[78:81], v[164:167], v[240:243], v[78:81]
	v_mfma_f32_16x16x32_bf16 v[74:77], v[174:177], v[240:243], v[74:77]
	v_mfma_f32_16x16x32_bf16 v[118:121], v[178:181], v[212:215], v[118:121]
	v_mfma_f32_16x16x32_bf16 v[114:117], v[204:207], v[212:215], v[114:117]
	v_mfma_f32_16x16x32_bf16 v[102:105], v[178:181], v[220:223], v[102:105]
	v_mfma_f32_16x16x32_bf16 v[98:101], v[204:207], v[220:223], v[98:101]
	v_mfma_f32_16x16x32_bf16 v[86:89], v[178:181], v[228:231], v[86:89]
	v_mfma_f32_16x16x32_bf16 v[82:85], v[204:207], v[228:231], v[82:85]
	v_mfma_f32_16x16x32_bf16 v[70:73], v[178:181], v[236:239], v[70:73]
	v_mfma_f32_16x16x32_bf16 v[66:69], v[204:207], v[236:239], v[66:69]
	v_mfma_f32_16x16x32_bf16 v[118:121], v[182:185], v[216:219], v[118:121]
	v_mfma_f32_16x16x32_bf16 v[114:117], v[208:211], v[216:219], v[114:117]
	v_mfma_f32_16x16x32_bf16 v[102:105], v[182:185], v[224:227], v[102:105]
	v_mfma_f32_16x16x32_bf16 v[98:101], v[208:211], v[224:227], v[98:101]
	v_mfma_f32_16x16x32_bf16 v[86:89], v[182:185], v[232:235], v[86:89]
	v_mfma_f32_16x16x32_bf16 v[82:85], v[208:211], v[232:235], v[82:85]
	v_mfma_f32_16x16x32_bf16 v[70:73], v[182:185], v[240:243], v[70:73]
	v_mfma_f32_16x16x32_bf16 v[66:69], v[208:211], v[240:243], v[66:69]
	s_setprio 0
	s_barrier
	s_add_i32 s36, s47, s4
	v_lshl_add_u64 v[186:187], s[18:19], 0, v[148:149]
	s_mov_b32 m0, s36
	ds_read_b128 v[212:215], v169 offset:16384
	ds_read_b128 v[216:219], v169 offset:17408
	ds_read_b128 v[220:223], v169 offset:18432
	ds_read_b128 v[224:227], v169 offset:19456
	ds_read_b128 v[228:231], v169 offset:20480
	ds_read_b128 v[232:235], v169 offset:21504
	ds_read_b128 v[236:239], v169 offset:22528
	ds_read_b128 v[240:243], v169 offset:23552
	global_load_lds_dwordx4 v[186:187], off
	s_add_i32 m0, s36, 0x2000
	s_add_u32 s36, s18, 0x60000
	v_lshl_add_u64 v[244:245], s[18:19], 0, v[144:145]
	s_addc_u32 s37, s19, 0
	s_add_i32 s47, s76, s4
	global_load_lds_dwordx4 v[244:245], off
	v_lshl_add_u64 v[246:247], s[36:37], 0, v[148:149]
	s_mov_b32 m0, s47
	v_lshl_add_u64 v[248:249], s[44:45], 0, v[146:147]
	global_load_lds_dwordx4 v[246:247], off
	v_lshl_add_u64 v[246:247], s[36:37], 0, v[144:145]
	s_add_i32 m0, s47, 0x2000
	s_nop 0
	global_load_lds_dwordx4 v[246:247], off
	v_lshl_add_u64 v[246:247], s[44:45], 0, v[150:151]
	s_mov_b32 m0, s54
	s_nop 0
	global_load_lds_dwordx4 v[246:247], off
	s_mov_b32 m0, s57
	s_nop 0
	global_load_lds_dwordx4 v[248:249], off
	s_waitcnt vmcnt(8)
	s_waitcnt lgkmcnt(0)
	s_setprio 1
	s_barrier
; #define PG8_STAGE(bufoff, gbase, voff) do { _Pragma("unroll") for (int _i = 0; _i < 2; ++_i) \
;         __builtin_amdgcn_global_load_lds((const unsigned*)((const char*)(gbase) + (voff)[_i]), (PG8_LAS unsigned*)(lds + (bufoff) + ldsw + _i * 8192), 16, 0, 0); } while (0)
; #define PG8_LDA(dst, b, h) do { _Pragma("unroll") for (int m = 0; m < 4; ++m) _Pragma("unroll") for (int k = 0; k < 2; ++k) dst[m][k] = *(const PG8_LAS bf16x8*)(lds + PG8_SA(b, h) + aoff + m * 2048 + k * 1024); } while (0)
; #define PG8_LDB(dst, b, h) do { _Pragma("unroll") for (int n = 0; n < 2; ++n) _Pragma("unroll") for (int k = 0; k < 2; ++k) dst[n][k] = *(const PG8_LAS bf16x8*)(lds + PG8_SB(b, h) + boff + n * 2048 + k * 1024); } while (0)
; #define PG8_MMA(ai, bj, At, Bt) do { __builtin_amdgcn_s_setprio(1); _Pragma("unroll") for (int m = 0; m < 4; ++m) _Pragma("unroll") for (int n = 0; n < 2; ++n) _Pragma("unroll") for (int k = 0; k < 2; ++k) \
;         acc[ai][bj][m][n] = __builtin_amdgcn_mfma_f32_16x16x32_bf16(Bt[n][k], At[m][k], acc[ai][bj][m][n], 0, 0, 0); __builtin_amdgcn_s_setprio(0); } while (0)
; #define PG8_WAIT_V(n) asm volatile("s_waitcnt vmcnt(" #n ")" ::: "memory")
; #define PG8_WAIT_L(n) asm volatile("s_waitcnt lgkmcnt(" #n ")" ::: "memory")
; #define PG8_BAR __builtin_amdgcn_s_barrier()
; #define PG8_SCHED __builtin_amdgcn_sched_barrier(0)
; template <class Epi, class Sched, bool ALIGN_EPI = false, bool SP2 = false>
; __device__ __forceinline__ void gemm_phase(PG8_LAS unsigned char* lds, const Gemm g, const Sched& S, const Epi& E) {
;     ...
;             PG8_WAIT_V(8); PG8_WAIT_L(0); PG8_BAR; PG8_MMA(1, 0, At, B0); PG8_MMA(1, 1, At, B1); PG8_BAR; PG8_SCHED;
;             PG8_LDB(B0, 1, 0); PG8_LDB(B1, 1, 1); PG8_SCHED; PG8_LDA(At, 1, 0); PG8_STAGE(PG8_SA(0, 1), a2 + hstep, voffA);
;             PG8_WAIT_V(8); PG8_WAIT_L(0); PG8_BAR; PG8_MMA(0, 0, At, B0); PG8_MMA(0, 1, At, B1); PG8_BAR; PG8_SCHED;
	v_mfma_f32_16x16x32_bf16 v[62:65], v[160:163], v[212:215], v[62:65]
	v_mfma_f32_16x16x32_bf16 v[58:61], v[170:173], v[212:215], v[58:61]
	v_mfma_f32_16x16x32_bf16 v[46:49], v[160:163], v[220:223], v[46:49]
	v_mfma_f32_16x16x32_bf16 v[42:45], v[170:173], v[220:223], v[42:45]
	v_mfma_f32_16x16x32_bf16 v[30:33], v[160:163], v[228:231], v[30:33]
	v_mfma_f32_16x16x32_bf16 v[26:29], v[170:173], v[228:231], v[26:29]
	v_mfma_f32_16x16x32_bf16 v[14:17], v[160:163], v[236:239], v[14:17]
	v_mfma_f32_16x16x32_bf16 v[10:13], v[170:173], v[236:239], v[10:13]
	v_mfma_f32_16x16x32_bf16 v[62:65], v[164:167], v[216:219], v[62:65]
	v_mfma_f32_16x16x32_bf16 v[58:61], v[174:177], v[216:219], v[58:61]
	v_mfma_f32_16x16x32_bf16 v[46:49], v[164:167], v[224:227], v[46:49]
	v_mfma_f32_16x16x32_bf16 v[42:45], v[174:177], v[224:227], v[42:45]
	v_mfma_f32_16x16x32_bf16 v[30:33], v[164:167], v[232:235], v[30:33]
	v_mfma_f32_16x16x32_bf16 v[26:29], v[174:177], v[232:235], v[26:29]
	v_mfma_f32_16x16x32_bf16 v[14:17], v[164:167], v[240:243], v[14:17]
	v_mfma_f32_16x16x32_bf16 v[10:13], v[174:177], v[240:243], v[10:13]
	v_mfma_f32_16x16x32_bf16 v[54:57], v[178:181], v[212:215], v[54:57]
	v_mfma_f32_16x16x32_bf16 v[50:53], v[204:207], v[212:215], v[50:53]
	v_mfma_f32_16x16x32_bf16 v[38:41], v[178:181], v[220:223], v[38:41]
	v_mfma_f32_16x16x32_bf16 v[34:37], v[204:207], v[220:223], v[34:37]
	v_mfma_f32_16x16x32_bf16 v[22:25], v[178:181], v[228:231], v[22:25]
	v_mfma_f32_16x16x32_bf16 v[18:21], v[204:207], v[228:231], v[18:21]
	v_mfma_f32_16x16x32_bf16 v[6:9], v[178:181], v[236:239], v[6:9]
	v_mfma_f32_16x16x32_bf16 v[2:5], v[204:207], v[236:239], v[2:5]
	v_mfma_f32_16x16x32_bf16 v[54:57], v[182:185], v[216:219], v[54:57]
	v_mfma_f32_16x16x32_bf16 v[50:53], v[208:211], v[216:219], v[50:53]
	v_mfma_f32_16x16x32_bf16 v[38:41], v[182:185], v[224:227], v[38:41]
	v_mfma_f32_16x16x32_bf16 v[34:37], v[208:211], v[224:227], v[34:37]
	v_mfma_f32_16x16x32_bf16 v[22:25], v[182:185], v[232:235], v[22:25]
	v_mfma_f32_16x16x32_bf16 v[18:21], v[208:211], v[232:235], v[18:21]
	v_mfma_f32_16x16x32_bf16 v[6:9], v[182:185], v[240:243], v[6:9]
	v_mfma_f32_16x16x32_bf16 v[2:5], v[208:211], v[240:243], v[2:5]
	s_setprio 0
	s_barrier
	s_add_i32 s47, 0, 0x18000
	s_add_i32 s76, 0, 0x1c000
	v_add_u32_e32 v174, s47, v143
	v_add_u32_e32 v203, s76, v143
	ds_read_b128 v[160:163], v174
	ds_read_b128 v[164:167], v174 offset:1024
	ds_read_b128 v[170:173], v174 offset:2048
	ds_read_b128 v[174:177], v174 offset:3072
	ds_read_b128 v[178:181], v203
	ds_read_b128 v[182:185], v203 offset:1024
	ds_read_b128 v[204:207], v203 offset:2048
	ds_read_b128 v[208:211], v203 offset:3072
	s_add_u32 s36, s44, 0x60000
	s_addc_u32 s37, s45, 0
	s_mov_b32 m0, s58
	v_lshl_add_u64 v[250:251], s[36:37], 0, v[150:151]
	ds_read_b128 v[212:215], v169 offset:32768
	ds_read_b128 v[216:219], v169 offset:33792
	ds_read_b128 v[220:223], v169 offset:34816
	ds_read_b128 v[224:227], v169 offset:35840
	ds_read_b128 v[228:231], v169 offset:36864
	ds_read_b128 v[232:235], v169 offset:37888
	ds_read_b128 v[236:239], v169 offset:38912
	ds_read_b128 v[240:243], v169 offset:39936
	global_load_lds_dwordx4 v[250:251], off
	v_lshl_add_u64 v[250:251], s[36:37], 0, v[146:147]
	s_mov_b32 m0, s59
	s_nop 0
	global_load_lds_dwordx4 v[250:251], off
	s_waitcnt vmcnt(8)
	s_waitcnt lgkmcnt(0)
	s_setprio 1
	s_barrier
	v_mfma_f32_16x16x32_bf16 v[126:129], v[160:163], v[212:215], v[126:129]
	v_mfma_f32_16x16x32_bf16 v[122:125], v[170:173], v[212:215], v[122:125]
	v_mfma_f32_16x16x32_bf16 v[110:113], v[160:163], v[220:223], v[110:113]
	v_mfma_f32_16x16x32_bf16 v[106:109], v[170:173], v[220:223], v[106:109]
	v_mfma_f32_16x16x32_bf16 v[94:97], v[160:163], v[228:231], v[94:97]
	v_mfma_f32_16x16x32_bf16 v[90:93], v[170:173], v[228:231], v[90:93]
	v_mfma_f32_16x16x32_bf16 v[78:81], v[160:163], v[236:239], v[78:81]
	v_mfma_f32_16x16x32_bf16 v[74:77], v[170:173], v[236:239], v[74:77]
	v_mfma_f32_16x16x32_bf16 v[126:129], v[164:167], v[216:219], v[126:129]
	v_mfma_f32_16x16x32_bf16 v[122:125], v[174:177], v[216:219], v[122:125]
	v_mfma_f32_16x16x32_bf16 v[110:113], v[164:167], v[224:227], v[110:113]
	v_mfma_f32_16x16x32_bf16 v[106:109], v[174:177], v[224:227], v[106:109]
	v_mfma_f32_16x16x32_bf16 v[94:97], v[164:167], v[232:235], v[94:97]
	v_mfma_f32_16x16x32_bf16 v[90:93], v[174:177], v[232:235], v[90:93]
	v_mfma_f32_16x16x32_bf16 v[78:81], v[164:167], v[240:243], v[78:81]
	v_mfma_f32_16x16x32_bf16 v[74:77], v[174:177], v[240:243], v[74:77]
	v_mfma_f32_16x16x32_bf16 v[118:121], v[178:181], v[212:215], v[118:121]
	v_mfma_f32_16x16x32_bf16 v[114:117], v[204:207], v[212:215], v[114:117]
	v_mfma_f32_16x16x32_bf16 v[102:105], v[178:181], v[220:223], v[102:105]
	v_mfma_f32_16x16x32_bf16 v[98:101], v[204:207], v[220:223], v[98:101]
	v_mfma_f32_16x16x32_bf16 v[86:89], v[178:181], v[228:231], v[86:89]
	v_mfma_f32_16x16x32_bf16 v[82:85], v[204:207], v[228:231], v[82:85]
	v_mfma_f32_16x16x32_bf16 v[70:73], v[178:181], v[236:239], v[70:73]
	v_mfma_f32_16x16x32_bf16 v[66:69], v[204:207], v[236:239], v[66:69]
	v_mfma_f32_16x16x32_bf16 v[118:121], v[182:185], v[216:219], v[118:121]
	v_mfma_f32_16x16x32_bf16 v[114:117], v[208:211], v[216:219], v[114:117]
	v_mfma_f32_16x16x32_bf16 v[102:105], v[182:185], v[224:227], v[102:105]
	v_mfma_f32_16x16x32_bf16 v[98:101], v[208:211], v[224:227], v[98:101]
	v_mfma_f32_16x16x32_bf16 v[86:89], v[182:185], v[232:235], v[86:89]
	v_mfma_f32_16x16x32_bf16 v[82:85], v[208:211], v[232:235], v[82:85]
	v_mfma_f32_16x16x32_bf16 v[70:73], v[182:185], v[240:243], v[70:73]
	v_mfma_f32_16x16x32_bf16 v[66:69], v[208:211], v[240:243], v[66:69]
	s_setprio 0
	s_barrier
; #define PG8_STAGE(bufoff, gbase, voff) do { _Pragma("unroll") for (int _i = 0; _i < 2; ++_i) \
;         __builtin_amdgcn_global_load_lds((const unsigned*)((const char*)(gbase) + (voff)[_i]), (PG8_LAS unsigned*)(lds + (bufoff) + ldsw + _i * 8192), 16, 0, 0); } while (0)
; #define PG8_LDA(dst, b, h) do { _Pragma("unroll") for (int m = 0; m < 4; ++m) _Pragma("unroll") for (int k = 0; k < 2; ++k) dst[m][k] = *(const PG8_LAS bf16x8*)(lds + PG8_SA(b, h) + aoff + m * 2048 + k * 1024); } while (0)
; #define PG8_MMA(ai, bj, At, Bt) do { __builtin_amdgcn_s_setprio(1); _Pragma("unroll") for (int m = 0; m < 4; ++m) _Pragma("unroll") for (int n = 0; n < 2; ++n) _Pragma("unroll") for (int k = 0; k < 2; ++k) \
;         acc[ai][bj][m][n] = __builtin_amdgcn_mfma_f32_16x16x32_bf16(Bt[n][k], At[m][k], acc[ai][bj][m][n], 0, 0, 0); __builtin_amdgcn_s_setprio(0); } while (0)
; #define PG8_WAIT_V(n) asm volatile("s_waitcnt vmcnt(" #n ")" ::: "memory")
; #define PG8_WAIT_L(n) asm volatile("s_waitcnt lgkmcnt(" #n ")" ::: "memory")
; #define PG8_BAR __builtin_amdgcn_s_barrier()
; #define PG8_SCHED __builtin_amdgcn_sched_barrier(0)
; template <class Epi, class Sched, bool ALIGN_EPI = false, bool SP2 = false>
; __device__ __forceinline__ void gemm_phase(PG8_LAS unsigned char* lds, const Gemm g, const Sched& S, const Epi& E) {
;     ...
;             PG8_LDA(At, 1, 1); PG8_STAGE(PG8_SB(1, 0), b3, voffB); PG8_STAGE(PG8_SB(1, 1), b3 + hstep, voffB); PG8_STAGE(PG8_SA(1, 0), a3, voffA);
;             PG8_WAIT_V(8); PG8_WAIT_L(0); PG8_BAR; PG8_MMA(1, 0, At, B0); PG8_MMA(1, 1, At, B1); PG8_BAR; PG8_SCHED;
	s_add_i32 s36, s47, s4
	v_lshl_add_u64 v[186:187], v[186:187], 0, s[68:69]
	s_mov_b32 m0, s36
	ds_read_b128 v[212:215], v169 offset:49152
	ds_read_b128 v[216:219], v169 offset:50176
	ds_read_b128 v[220:223], v169 offset:51200
	ds_read_b128 v[224:227], v169 offset:52224
	ds_read_b128 v[228:231], v169 offset:53248
	ds_read_b128 v[232:235], v169 offset:54272
	ds_read_b128 v[236:239], v169 offset:55296
	ds_read_b128 v[240:243], v169 offset:56320
	global_load_lds_dwordx4 v[186:187], off
	s_add_i32 m0, s36, 0x2000
	s_add_u32 s18, s18, 0x60080
	v_lshl_add_u64 v[186:187], v[244:245], 0, s[68:69]
	s_addc_u32 s19, s19, 0
	s_add_i32 s36, s76, s4
	global_load_lds_dwordx4 v[186:187], off
	v_lshl_add_u64 v[186:187], s[18:19], 0, v[148:149]
	s_mov_b32 m0, s36
	s_nop 0
	global_load_lds_dwordx4 v[186:187], off
	v_lshl_add_u64 v[186:187], s[18:19], 0, v[144:145]
	s_add_i32 m0, s36, 0x2000
	s_nop 0
	global_load_lds_dwordx4 v[186:187], off
	v_lshl_add_u64 v[186:187], v[246:247], 0, s[68:69]
	s_mov_b32 m0, s62
	s_nop 0
	global_load_lds_dwordx4 v[186:187], off
	v_lshl_add_u64 v[186:187], v[248:249], 0, s[68:69]
	s_mov_b32 m0, s63
	s_nop 0
	global_load_lds_dwordx4 v[186:187], off
	s_nop 0
	s_waitcnt vmcnt(8)
	s_waitcnt lgkmcnt(0)
	s_setprio 1
	s_barrier
	v_mfma_f32_16x16x32_bf16 v[62:65], v[160:163], v[212:215], v[62:65]
	v_mfma_f32_16x16x32_bf16 v[58:61], v[170:173], v[212:215], v[58:61]
	v_mfma_f32_16x16x32_bf16 v[46:49], v[160:163], v[220:223], v[46:49]
	v_mfma_f32_16x16x32_bf16 v[42:45], v[170:173], v[220:223], v[42:45]
	v_mfma_f32_16x16x32_bf16 v[30:33], v[160:163], v[228:231], v[30:33]
	v_mfma_f32_16x16x32_bf16 v[26:29], v[170:173], v[228:231], v[26:29]
	v_mfma_f32_16x16x32_bf16 v[14:17], v[160:163], v[236:239], v[14:17]
	v_mfma_f32_16x16x32_bf16 v[10:13], v[170:173], v[236:239], v[10:13]
	v_mfma_f32_16x16x32_bf16 v[62:65], v[164:167], v[216:219], v[62:65]
	v_mfma_f32_16x16x32_bf16 v[58:61], v[174:177], v[216:219], v[58:61]
	v_mfma_f32_16x16x32_bf16 v[46:49], v[164:167], v[224:227], v[46:49]
	v_mfma_f32_16x16x32_bf16 v[42:45], v[174:177], v[224:227], v[42:45]
	v_mfma_f32_16x16x32_bf16 v[30:33], v[164:167], v[232:235], v[30:33]
	v_mfma_f32_16x16x32_bf16 v[26:29], v[174:177], v[232:235], v[26:29]
	v_mfma_f32_16x16x32_bf16 v[14:17], v[164:167], v[240:243], v[14:17]
	v_mfma_f32_16x16x32_bf16 v[10:13], v[174:177], v[240:243], v[10:13]
	v_mfma_f32_16x16x32_bf16 v[54:57], v[178:181], v[212:215], v[54:57]
	v_mfma_f32_16x16x32_bf16 v[50:53], v[204:207], v[212:215], v[50:53]
	v_mfma_f32_16x16x32_bf16 v[38:41], v[178:181], v[220:223], v[38:41]
	v_mfma_f32_16x16x32_bf16 v[34:37], v[204:207], v[220:223], v[34:37]
	v_mfma_f32_16x16x32_bf16 v[22:25], v[178:181], v[228:231], v[22:25]
	v_mfma_f32_16x16x32_bf16 v[18:21], v[204:207], v[228:231], v[18:21]
	v_mfma_f32_16x16x32_bf16 v[6:9], v[178:181], v[236:239], v[6:9]
	v_mfma_f32_16x16x32_bf16 v[2:5], v[204:207], v[236:239], v[2:5]
	v_mfma_f32_16x16x32_bf16 v[54:57], v[182:185], v[216:219], v[54:57]
	v_mfma_f32_16x16x32_bf16 v[50:53], v[208:211], v[216:219], v[50:53]
	v_mfma_f32_16x16x32_bf16 v[38:41], v[182:185], v[224:227], v[38:41]
	v_mfma_f32_16x16x32_bf16 v[34:37], v[208:211], v[224:227], v[34:37]
	v_mfma_f32_16x16x32_bf16 v[22:25], v[182:185], v[232:235], v[22:25]
	v_mfma_f32_16x16x32_bf16 v[18:21], v[208:211], v[232:235], v[18:21]
	v_mfma_f32_16x16x32_bf16 v[6:9], v[182:185], v[240:243], v[6:9]
	v_mfma_f32_16x16x32_bf16 v[2:5], v[208:211], v[240:243], v[2:5]
	s_setprio 0
	s_barrier
	s_add_i32 s46, s46, 2
	s_add_u32 s60, s60, 0x100
	s_addc_u32 s73, s73, 0
	s_cmp_gt_u32 s46, 21
	s_mov_b64 s[36:37], s[42:43]
	s_cbranch_scc0 .LBB0_160
	s_and_b64 vcc, exec, s[10:11]
	s_cbranch_vccz .LBB0_163
	s_barrier

; #define PG8_STAGE(bufoff, gbase, voff) do { _Pragma("unroll") for (int _i = 0; _i < 2; ++_i) \
;         __builtin_amdgcn_global_load_lds((const unsigned*)((const char*)(gbase) + (voff)[_i]), (PG8_LAS unsigned*)(lds + (bufoff) + ldsw + _i * 8192), 16, 0, 0); } while (0)
; #define PG8_LDA(dst, b, h) do { _Pragma("unroll") for (int m = 0; m < 4; ++m) _Pragma("unroll") for (int k = 0; k < 2; ++k) dst[m][k] = *(const PG8_LAS bf16x8*)(lds + PG8_SA(b, h) + aoff + m * 2048 + k * 1024); } while (0)
; #define PG8_LDB(dst, b, h) do { _Pragma("unroll") for (int n = 0; n < 2; ++n) _Pragma("unroll") for (int k = 0; k < 2; ++k) dst[n][k] = *(const PG8_LAS bf16x8*)(lds + PG8_SB(b, h) + boff + n * 2048 + k * 1024); } while (0)
; #define PG8_MMA(ai, bj, At, Bt) do { __builtin_amdgcn_s_setprio(1); _Pragma("unroll") for (int m = 0; m < 4; ++m) _Pragma("unroll") for (int n = 0; n < 2; ++n) _Pragma("unroll") for (int k = 0; k < 2; ++k) \
;         acc[ai][bj][m][n] = __builtin_amdgcn_mfma_f32_16x16x32_bf16(Bt[n][k], At[m][k], acc[ai][bj][m][n], 0, 0, 0); __builtin_amdgcn_s_setprio(0); } while (0)
; #define PG8_WAIT_V(n) asm volatile("s_waitcnt vmcnt(" #n ")" ::: "memory")
; #define PG8_WAIT_L(n) asm volatile("s_waitcnt lgkmcnt(" #n ")" ::: "memory")
; #define PG8_BAR __builtin_amdgcn_s_barrier()
; #define PG8_SCHED __builtin_amdgcn_sched_barrier(0)
; template <class Epi, class Sched, bool ALIGN_EPI = false, bool SP2 = false>
; __device__ __forceinline__ void gemm_phase(PG8_LAS unsigned char* lds, const Gemm g, const Sched& S, const Epi& E) {
;     ...
;             const bool last = (t == nt - 2);
;             const char* a1 = cA + (size_t)(t + 1) * kstep;
;             const char* a2 = last ? nA : cA + (size_t)(t + 2) * kstep; const char* b2 = last ? nB : cB + (size_t)(t + 2) * kstep;
;             const char* a3 = a2 + kstep; const char* b3 = b2 + kstep;
;             if (last && has_next) S.a_ready(nxt);
;             if constexpr (SP2) {
;             PG8_LDB(B0, 0, 0); PG8_LDB(B1, 0, 1); PG8_SCHED; PG8_LDA(At, 0, 0); PG8_STAGE(PG8_SA(1, 1), a1 + hstep, voffA);
;             PG8_WAIT_V(8); PG8_WAIT_L(0); PG8_BAR; PG8_MMA(0, 0, At, B0); PG8_MMA(0, 1, At, B1); PG8_BAR; PG8_SCHED;
;             PG8_LDA(At, 0, 1); PG8_STAGE(PG8_SB(0, 0), b2, voffB); PG8_STAGE(PG8_SB(0, 1), b2 + hstep, voffB); PG8_STAGE(PG8_SA(0, 0), a2, voffA);
.LBB0_281:
	s_add_u32 s18, s36, 0xfff80080
	s_addc_u32 s19, s37, -1
	s_add_i32 s73, 0, 0x10000
	s_cmp_eq_u32 s67, 28
	s_cselect_b32 s43, s9, s19
	s_cselect_b32 s42, s59, s18
	v_add_u32_e32 v163, s73, v160
	s_cselect_b32 s19, s7, s63
	s_cselect_b32 s18, s60, s62
	s_add_i32 s76, 0, 0x14000
	ds_read_b128 v[156:159], v163
	ds_read_b128 v[164:167], v163 offset:1024
	ds_read_b128 v[168:171], v163 offset:2048
	ds_read_b128 v[172:175], v163 offset:3072
	v_add_u32_e32 v163, s76, v160
	ds_read_b128 v[176:179], v163
	ds_read_b128 v[180:183], v163 offset:1024
	ds_read_b128 v[184:187], v163 offset:2048
	ds_read_b128 v[204:207], v163 offset:3072
	v_lshl_add_u64 v[240:241], s[36:37], 0, v[152:153]
	s_add_i32 m0, s30, 0xc000
	ds_read_b128 v[208:211], v162
	ds_read_b128 v[212:215], v162 offset:1024
	ds_read_b128 v[216:219], v162 offset:2048
	ds_read_b128 v[220:223], v162 offset:3072
	ds_read_b128 v[224:227], v162 offset:4096
	ds_read_b128 v[228:231], v162 offset:5120
	ds_read_b128 v[232:235], v162 offset:6144
	ds_read_b128 v[236:239], v162 offset:7168
	global_load_lds_dwordx4 v[240:241], off
	v_lshl_add_u64 v[240:241], s[36:37], 0, v[154:155]
	s_add_i32 m0, s30, 0xe000
	s_nop 0
	global_load_lds_dwordx4 v[240:241], off
	s_nop 0
	s_nop 0
	s_waitcnt vmcnt(8)
	s_waitcnt lgkmcnt(0)
	s_setprio 1
	s_barrier
	v_mfma_f32_16x16x32_bf16 v[126:129], v[156:159], v[208:211], v[126:129]
	v_mfma_f32_16x16x32_bf16 v[122:125], v[168:171], v[208:211], v[122:125]
	v_mfma_f32_16x16x32_bf16 v[110:113], v[156:159], v[216:219], v[110:113]
	v_mfma_f32_16x16x32_bf16 v[106:109], v[168:171], v[216:219], v[106:109]
	v_mfma_f32_16x16x32_bf16 v[94:97], v[156:159], v[224:227], v[94:97]
	v_mfma_f32_16x16x32_bf16 v[90:93], v[168:171], v[224:227], v[90:93]
	v_mfma_f32_16x16x32_bf16 v[78:81], v[156:159], v[232:235], v[78:81]
	v_mfma_f32_16x16x32_bf16 v[74:77], v[168:171], v[232:235], v[74:77]
	v_mfma_f32_16x16x32_bf16 v[126:129], v[164:167], v[212:215], v[126:129]
	v_mfma_f32_16x16x32_bf16 v[122:125], v[172:175], v[212:215], v[122:125]
	v_mfma_f32_16x16x32_bf16 v[110:113], v[164:167], v[220:223], v[110:113]
	v_mfma_f32_16x16x32_bf16 v[106:109], v[172:175], v[220:223], v[106:109]
	v_mfma_f32_16x16x32_bf16 v[94:97], v[164:167], v[228:231], v[94:97]
	v_mfma_f32_16x16x32_bf16 v[90:93], v[172:175], v[228:231], v[90:93]
	v_mfma_f32_16x16x32_bf16 v[78:81], v[164:167], v[236:239], v[78:81]
	v_mfma_f32_16x16x32_bf16 v[74:77], v[172:175], v[236:239], v[74:77]
	v_mfma_f32_16x16x32_bf16 v[118:121], v[176:179], v[208:211], v[118:121]
	v_mfma_f32_16x16x32_bf16 v[114:117], v[184:187], v[208:211], v[114:117]
	v_mfma_f32_16x16x32_bf16 v[102:105], v[176:179], v[216:219], v[102:105]
	v_mfma_f32_16x16x32_bf16 v[98:101], v[184:187], v[216:219], v[98:101]
	v_mfma_f32_16x16x32_bf16 v[86:89], v[176:179], v[224:227], v[86:89]
	v_mfma_f32_16x16x32_bf16 v[82:85], v[184:187], v[224:227], v[82:85]
	v_mfma_f32_16x16x32_bf16 v[70:73], v[176:179], v[232:235], v[70:73]
	v_mfma_f32_16x16x32_bf16 v[66:69], v[184:187], v[232:235], v[66:69]
	v_mfma_f32_16x16x32_bf16 v[118:121], v[180:183], v[212:215], v[118:121]
	v_mfma_f32_16x16x32_bf16 v[114:117], v[204:207], v[212:215], v[114:117]
	v_mfma_f32_16x16x32_bf16 v[102:105], v[180:183], v[220:223], v[102:105]
	v_mfma_f32_16x16x32_bf16 v[98:101], v[204:207], v[220:223], v[98:101]
	v_mfma_f32_16x16x32_bf16 v[86:89], v[180:183], v[228:231], v[86:89]
	v_mfma_f32_16x16x32_bf16 v[82:85], v[204:207], v[228:231], v[82:85]
	v_mfma_f32_16x16x32_bf16 v[70:73], v[180:183], v[236:239], v[70:73]
	v_mfma_f32_16x16x32_bf16 v[66:69], v[204:207], v[236:239], v[66:69]
	s_setprio 0
	s_barrier
	s_add_i32 s73, s73, s28
	v_lshl_add_u64 v[240:241], s[18:19], 0, v[146:147]
	s_mov_b32 m0, s73
	ds_read_b128 v[208:211], v162 offset:16384
	ds_read_b128 v[212:215], v162 offset:17408
	ds_read_b128 v[216:219], v162 offset:18432
	ds_read_b128 v[220:223], v162 offset:19456
	ds_read_b128 v[224:227], v162 offset:20480
	ds_read_b128 v[228:231], v162 offset:21504
	ds_read_b128 v[232:235], v162 offset:22528
	ds_read_b128 v[236:239], v162 offset:23552
	global_load_lds_dwordx4 v[240:241], off
	s_add_i32 m0, s73, 0x2000
	s_add_u32 s78, s18, 0x80000
	v_lshl_add_u64 v[242:243], s[18:19], 0, v[142:143]
	s_addc_u32 s79, s19, 0
	s_add_i32 s73, s76, s28
	global_load_lds_dwordx4 v[242:243], off
	v_lshl_add_u64 v[244:245], s[78:79], 0, v[146:147]
	s_mov_b32 m0, s73
	v_lshl_add_u64 v[246:247], s[42:43], 0, v[144:145]
	global_load_lds_dwordx4 v[244:245], off
	v_lshl_add_u64 v[244:245], s[78:79], 0, v[142:143]
	s_add_i32 m0, s73, 0x2000
	s_nop 0
	global_load_lds_dwordx4 v[244:245], off
	v_lshl_add_u64 v[244:245], s[42:43], 0, v[148:149]
	s_mov_b32 m0, s30
	s_nop 0
	global_load_lds_dwordx4 v[244:245], off
	s_mov_b32 m0, s34
	s_nop 0
	global_load_lds_dwordx4 v[246:247], off
	s_waitcnt vmcnt(8)
	s_waitcnt lgkmcnt(0)
	s_setprio 1
	s_barrier
; #define PG8_STAGE(bufoff, gbase, voff) do { _Pragma("unroll") for (int _i = 0; _i < 2; ++_i) \
;         __builtin_amdgcn_global_load_lds((const unsigned*)((const char*)(gbase) + (voff)[_i]), (PG8_LAS unsigned*)(lds + (bufoff) + ldsw + _i * 8192), 16, 0, 0); } while (0)
; #define PG8_LDA(dst, b, h) do { _Pragma("unroll") for (int m = 0; m < 4; ++m) _Pragma("unroll") for (int k = 0; k < 2; ++k) dst[m][k] = *(const PG8_LAS bf16x8*)(lds + PG8_SA(b, h) + aoff + m * 2048 + k * 1024); } while (0)
; #define PG8_LDB(dst, b, h) do { _Pragma("unroll") for (int n = 0; n < 2; ++n) _Pragma("unroll") for (int k = 0; k < 2; ++k) dst[n][k] = *(const PG8_LAS bf16x8*)(lds + PG8_SB(b, h) + boff + n * 2048 + k * 1024); } while (0)
; #define PG8_MMA(ai, bj, At, Bt) do { __builtin_amdgcn_s_setprio(1); _Pragma("unroll") for (int m = 0; m < 4; ++m) _Pragma("unroll") for (int n = 0; n < 2; ++n) _Pragma("unroll") for (int k = 0; k < 2; ++k) \
;         acc[ai][bj][m][n] = __builtin_amdgcn_mfma_f32_16x16x32_bf16(Bt[n][k], At[m][k], acc[ai][bj][m][n], 0, 0, 0); __builtin_amdgcn_s_setprio(0); } while (0)
; #define PG8_WAIT_V(n) asm volatile("s_waitcnt vmcnt(" #n ")" ::: "memory")
; #define PG8_WAIT_L(n) asm volatile("s_waitcnt lgkmcnt(" #n ")" ::: "memory")
; #define PG8_BAR __builtin_amdgcn_s_barrier()
; #define PG8_SCHED __builtin_amdgcn_sched_barrier(0)
; template <class Epi, class Sched, bool ALIGN_EPI = false, bool SP2 = false>
; __device__ __forceinline__ void gemm_phase(PG8_LAS unsigned char* lds, const Gemm g, const Sched& S, const Epi& E) {
;     ...
;             PG8_WAIT_V(8); PG8_WAIT_L(0); PG8_BAR; PG8_MMA(1, 0, At, B0); PG8_MMA(1, 1, At, B1); PG8_BAR; PG8_SCHED;
;             PG8_LDB(B0, 1, 0); PG8_LDB(B1, 1, 1); PG8_SCHED; PG8_LDA(At, 1, 0); PG8_STAGE(PG8_SA(0, 1), a2 + hstep, voffA);
;             PG8_WAIT_V(8); PG8_WAIT_L(0); PG8_BAR; PG8_MMA(0, 0, At, B0); PG8_MMA(0, 1, At, B1); PG8_BAR; PG8_SCHED;
	v_mfma_f32_16x16x32_bf16 v[62:65], v[156:159], v[208:211], v[62:65]
	v_mfma_f32_16x16x32_bf16 v[58:61], v[168:171], v[208:211], v[58:61]
	v_mfma_f32_16x16x32_bf16 v[46:49], v[156:159], v[216:219], v[46:49]
	v_mfma_f32_16x16x32_bf16 v[42:45], v[168:171], v[216:219], v[42:45]
	v_mfma_f32_16x16x32_bf16 v[30:33], v[156:159], v[224:227], v[30:33]
	v_mfma_f32_16x16x32_bf16 v[26:29], v[168:171], v[224:227], v[26:29]
	v_mfma_f32_16x16x32_bf16 v[14:17], v[156:159], v[232:235], v[14:17]
	v_mfma_f32_16x16x32_bf16 v[10:13], v[168:171], v[232:235], v[10:13]
	v_mfma_f32_16x16x32_bf16 v[62:65], v[164:167], v[212:215], v[62:65]
	v_mfma_f32_16x16x32_bf16 v[58:61], v[172:175], v[212:215], v[58:61]
	v_mfma_f32_16x16x32_bf16 v[46:49], v[164:167], v[220:223], v[46:49]
	v_mfma_f32_16x16x32_bf16 v[42:45], v[172:175], v[220:223], v[42:45]
	v_mfma_f32_16x16x32_bf16 v[30:33], v[164:167], v[228:231], v[30:33]
	v_mfma_f32_16x16x32_bf16 v[26:29], v[172:175], v[228:231], v[26:29]
	v_mfma_f32_16x16x32_bf16 v[14:17], v[164:167], v[236:239], v[14:17]
	v_mfma_f32_16x16x32_bf16 v[10:13], v[172:175], v[236:239], v[10:13]
	v_mfma_f32_16x16x32_bf16 v[54:57], v[176:179], v[208:211], v[54:57]
	v_mfma_f32_16x16x32_bf16 v[50:53], v[184:187], v[208:211], v[50:53]
	v_mfma_f32_16x16x32_bf16 v[38:41], v[176:179], v[216:219], v[38:41]
	v_mfma_f32_16x16x32_bf16 v[34:37], v[184:187], v[216:219], v[34:37]
	v_mfma_f32_16x16x32_bf16 v[22:25], v[176:179], v[224:227], v[22:25]
	v_mfma_f32_16x16x32_bf16 v[18:21], v[184:187], v[224:227], v[18:21]
	v_mfma_f32_16x16x32_bf16 v[6:9], v[176:179], v[232:235], v[6:9]
	v_mfma_f32_16x16x32_bf16 v[2:5], v[184:187], v[232:235], v[2:5]
	v_mfma_f32_16x16x32_bf16 v[54:57], v[180:183], v[212:215], v[54:57]
	v_mfma_f32_16x16x32_bf16 v[50:53], v[204:207], v[212:215], v[50:53]
	v_mfma_f32_16x16x32_bf16 v[38:41], v[180:183], v[220:223], v[38:41]
	v_mfma_f32_16x16x32_bf16 v[34:37], v[204:207], v[220:223], v[34:37]
	v_mfma_f32_16x16x32_bf16 v[22:25], v[180:183], v[228:231], v[22:25]
	v_mfma_f32_16x16x32_bf16 v[18:21], v[204:207], v[228:231], v[18:21]
	v_mfma_f32_16x16x32_bf16 v[6:9], v[180:183], v[236:239], v[6:9]
	v_mfma_f32_16x16x32_bf16 v[2:5], v[204:207], v[236:239], v[2:5]
	s_setprio 0
	s_barrier
	s_add_i32 s73, 0, 0x18000
	v_add_u32_e32 v163, s73, v160
	s_add_i32 s76, 0, 0x1c000
	ds_read_b128 v[156:159], v163
	ds_read_b128 v[164:167], v163 offset:1024
	ds_read_b128 v[168:171], v163 offset:2048
	ds_read_b128 v[172:175], v163 offset:3072
	v_add_u32_e32 v163, s76, v160
	ds_read_b128 v[176:179], v163
	ds_read_b128 v[180:183], v163 offset:1024
	ds_read_b128 v[184:187], v163 offset:2048
	ds_read_b128 v[204:207], v163 offset:3072
	s_add_u32 s42, s42, 0x80000
	s_addc_u32 s43, s43, 0
	s_mov_b32 m0, s44
	v_lshl_add_u64 v[248:249], s[42:43], 0, v[148:149]
	ds_read_b128 v[208:211], v162 offset:32768
	ds_read_b128 v[212:215], v162 offset:33792
	ds_read_b128 v[216:219], v162 offset:34816
	ds_read_b128 v[220:223], v162 offset:35840
	ds_read_b128 v[224:227], v162 offset:36864
	ds_read_b128 v[228:231], v162 offset:37888
	ds_read_b128 v[232:235], v162 offset:38912
	ds_read_b128 v[236:239], v162 offset:39936
	global_load_lds_dwordx4 v[248:249], off
	v_lshl_add_u64 v[248:249], s[42:43], 0, v[144:145]
	s_mov_b32 m0, s45
	s_nop 0
	global_load_lds_dwordx4 v[248:249], off
	s_waitcnt vmcnt(8)
	s_waitcnt lgkmcnt(0)
	s_setprio 1
	s_barrier
	v_mfma_f32_16x16x32_bf16 v[126:129], v[156:159], v[208:211], v[126:129]
	v_mfma_f32_16x16x32_bf16 v[122:125], v[168:171], v[208:211], v[122:125]
	v_mfma_f32_16x16x32_bf16 v[110:113], v[156:159], v[216:219], v[110:113]
	v_mfma_f32_16x16x32_bf16 v[106:109], v[168:171], v[216:219], v[106:109]
	v_mfma_f32_16x16x32_bf16 v[94:97], v[156:159], v[224:227], v[94:97]
	v_mfma_f32_16x16x32_bf16 v[90:93], v[168:171], v[224:227], v[90:93]
	v_mfma_f32_16x16x32_bf16 v[78:81], v[156:159], v[232:235], v[78:81]
	v_mfma_f32_16x16x32_bf16 v[74:77], v[168:171], v[232:235], v[74:77]
	v_mfma_f32_16x16x32_bf16 v[126:129], v[164:167], v[212:215], v[126:129]
	v_mfma_f32_16x16x32_bf16 v[122:125], v[172:175], v[212:215], v[122:125]
	v_mfma_f32_16x16x32_bf16 v[110:113], v[164:167], v[220:223], v[110:113]
	v_mfma_f32_16x16x32_bf16 v[106:109], v[172:175], v[220:223], v[106:109]
	v_mfma_f32_16x16x32_bf16 v[94:97], v[164:167], v[228:231], v[94:97]
	v_mfma_f32_16x16x32_bf16 v[90:93], v[172:175], v[228:231], v[90:93]
	v_mfma_f32_16x16x32_bf16 v[78:81], v[164:167], v[236:239], v[78:81]
	v_mfma_f32_16x16x32_bf16 v[74:77], v[172:175], v[236:239], v[74:77]
	v_mfma_f32_16x16x32_bf16 v[118:121], v[176:179], v[208:211], v[118:121]
	v_mfma_f32_16x16x32_bf16 v[114:117], v[184:187], v[208:211], v[114:117]
	v_mfma_f32_16x16x32_bf16 v[102:105], v[176:179], v[216:219], v[102:105]
	v_mfma_f32_16x16x32_bf16 v[98:101], v[184:187], v[216:219], v[98:101]
	v_mfma_f32_16x16x32_bf16 v[86:89], v[176:179], v[224:227], v[86:89]
	v_mfma_f32_16x16x32_bf16 v[82:85], v[184:187], v[224:227], v[82:85]
	v_mfma_f32_16x16x32_bf16 v[70:73], v[176:179], v[232:235], v[70:73]
	v_mfma_f32_16x16x32_bf16 v[66:69], v[184:187], v[232:235], v[66:69]
	v_mfma_f32_16x16x32_bf16 v[118:121], v[180:183], v[212:215], v[118:121]
	v_mfma_f32_16x16x32_bf16 v[114:117], v[204:207], v[212:215], v[114:117]
	v_mfma_f32_16x16x32_bf16 v[102:105], v[180:183], v[220:223], v[102:105]
	v_mfma_f32_16x16x32_bf16 v[98:101], v[204:207], v[220:223], v[98:101]
	v_mfma_f32_16x16x32_bf16 v[86:89], v[180:183], v[228:231], v[86:89]
	v_mfma_f32_16x16x32_bf16 v[82:85], v[204:207], v[228:231], v[82:85]
	v_mfma_f32_16x16x32_bf16 v[70:73], v[180:183], v[236:239], v[70:73]
	v_mfma_f32_16x16x32_bf16 v[66:69], v[204:207], v[236:239], v[66:69]
	s_setprio 0
	s_barrier
; #define PG8_STAGE(bufoff, gbase, voff) do { _Pragma("unroll") for (int _i = 0; _i < 2; ++_i) \
;         __builtin_amdgcn_global_load_lds((const unsigned*)((const char*)(gbase) + (voff)[_i]), (PG8_LAS unsigned*)(lds + (bufoff) + ldsw + _i * 8192), 16, 0, 0); } while (0)
; #define PG8_LDA(dst, b, h) do { _Pragma("unroll") for (int m = 0; m < 4; ++m) _Pragma("unroll") for (int k = 0; k < 2; ++k) dst[m][k] = *(const PG8_LAS bf16x8*)(lds + PG8_SA(b, h) + aoff + m * 2048 + k * 1024); } while (0)
; #define PG8_MMA(ai, bj, At, Bt) do { __builtin_amdgcn_s_setprio(1); _Pragma("unroll") for (int m = 0; m < 4; ++m) _Pragma("unroll") for (int n = 0; n < 2; ++n) _Pragma("unroll") for (int k = 0; k < 2; ++k) \
;         acc[ai][bj][m][n] = __builtin_amdgcn_mfma_f32_16x16x32_bf16(Bt[n][k], At[m][k], acc[ai][bj][m][n], 0, 0, 0); __builtin_amdgcn_s_setprio(0); } while (0)
; #define PG8_WAIT_V(n) asm volatile("s_waitcnt vmcnt(" #n ")" ::: "memory")
; #define PG8_WAIT_L(n) asm volatile("s_waitcnt lgkmcnt(" #n ")" ::: "memory")
; #define PG8_BAR __builtin_amdgcn_s_barrier()
; #define PG8_SCHED __builtin_amdgcn_sched_barrier(0)
; template <class Epi, class Sched, bool ALIGN_EPI = false, bool SP2 = false>
; __device__ __forceinline__ void gemm_phase(PG8_LAS unsigned char* lds, const Gemm g, const Sched& S, const Epi& E) {
;     ...
;             PG8_LDA(At, 1, 1); PG8_STAGE(PG8_SB(1, 0), b3, voffB); PG8_STAGE(PG8_SB(1, 1), b3 + hstep, voffB); PG8_STAGE(PG8_SA(1, 0), a3, voffA);
;             PG8_WAIT_V(8); PG8_WAIT_L(0); PG8_BAR; PG8_MMA(1, 0, At, B0); PG8_MMA(1, 1, At, B1); PG8_BAR; PG8_SCHED;
	s_add_i32 s42, s73, s28
	v_lshl_add_u64 v[240:241], v[240:241], 0, s[68:69]
	s_mov_b32 m0, s42
	ds_read_b128 v[208:211], v162 offset:49152
	ds_read_b128 v[212:215], v162 offset:50176
	ds_read_b128 v[216:219], v162 offset:51200
	ds_read_b128 v[220:223], v162 offset:52224
	ds_read_b128 v[224:227], v162 offset:53248
	ds_read_b128 v[228:231], v162 offset:54272
	ds_read_b128 v[232:235], v162 offset:55296
	ds_read_b128 v[236:239], v162 offset:56320
	global_load_lds_dwordx4 v[240:241], off
	s_add_i32 m0, s42, 0x2000
	s_add_u32 s18, s18, 0x80080
	v_lshl_add_u64 v[240:241], v[242:243], 0, s[68:69]
	s_addc_u32 s19, s19, 0
	s_add_i32 s42, s76, s28
	global_load_lds_dwordx4 v[240:241], off
	v_lshl_add_u64 v[240:241], s[18:19], 0, v[146:147]
	s_mov_b32 m0, s42
	s_nop 0
	global_load_lds_dwordx4 v[240:241], off
	v_lshl_add_u64 v[240:241], s[18:19], 0, v[142:143]
	s_add_i32 m0, s42, 0x2000
	s_nop 0
	global_load_lds_dwordx4 v[240:241], off
	v_lshl_add_u64 v[240:241], v[244:245], 0, s[68:69]
	s_mov_b32 m0, s46
	s_nop 0
	global_load_lds_dwordx4 v[240:241], off
	v_lshl_add_u64 v[240:241], v[246:247], 0, s[68:69]
	s_mov_b32 m0, s47
	s_nop 0
	global_load_lds_dwordx4 v[240:241], off
	s_nop 0
	s_waitcnt vmcnt(8)
	s_waitcnt lgkmcnt(0)
	s_setprio 1
	s_barrier
	v_mfma_f32_16x16x32_bf16 v[62:65], v[156:159], v[208:211], v[62:65]
	v_mfma_f32_16x16x32_bf16 v[58:61], v[168:171], v[208:211], v[58:61]
	v_mfma_f32_16x16x32_bf16 v[46:49], v[156:159], v[216:219], v[46:49]
	v_mfma_f32_16x16x32_bf16 v[42:45], v[168:171], v[216:219], v[42:45]
	v_mfma_f32_16x16x32_bf16 v[30:33], v[156:159], v[224:227], v[30:33]
	v_mfma_f32_16x16x32_bf16 v[26:29], v[168:171], v[224:227], v[26:29]
	v_mfma_f32_16x16x32_bf16 v[14:17], v[156:159], v[232:235], v[14:17]
	v_mfma_f32_16x16x32_bf16 v[10:13], v[168:171], v[232:235], v[10:13]
	v_mfma_f32_16x16x32_bf16 v[62:65], v[164:167], v[212:215], v[62:65]
	v_mfma_f32_16x16x32_bf16 v[58:61], v[172:175], v[212:215], v[58:61]
	v_mfma_f32_16x16x32_bf16 v[46:49], v[164:167], v[220:223], v[46:49]
	v_mfma_f32_16x16x32_bf16 v[42:45], v[172:175], v[220:223], v[42:45]
	v_mfma_f32_16x16x32_bf16 v[30:33], v[164:167], v[228:231], v[30:33]
	v_mfma_f32_16x16x32_bf16 v[26:29], v[172:175], v[228:231], v[26:29]
	v_mfma_f32_16x16x32_bf16 v[14:17], v[164:167], v[236:239], v[14:17]
	v_mfma_f32_16x16x32_bf16 v[10:13], v[172:175], v[236:239], v[10:13]
	v_mfma_f32_16x16x32_bf16 v[54:57], v[176:179], v[208:211], v[54:57]
	v_mfma_f32_16x16x32_bf16 v[50:53], v[184:187], v[208:211], v[50:53]
	v_mfma_f32_16x16x32_bf16 v[38:41], v[176:179], v[216:219], v[38:41]
	v_mfma_f32_16x16x32_bf16 v[34:37], v[184:187], v[216:219], v[34:37]
	v_mfma_f32_16x16x32_bf16 v[22:25], v[176:179], v[224:227], v[22:25]
	v_mfma_f32_16x16x32_bf16 v[18:21], v[184:187], v[224:227], v[18:21]
	v_mfma_f32_16x16x32_bf16 v[6:9], v[176:179], v[232:235], v[6:9]
	v_mfma_f32_16x16x32_bf16 v[2:5], v[184:187], v[232:235], v[2:5]
	v_mfma_f32_16x16x32_bf16 v[54:57], v[180:183], v[212:215], v[54:57]
	v_mfma_f32_16x16x32_bf16 v[50:53], v[204:207], v[212:215], v[50:53]
	v_mfma_f32_16x16x32_bf16 v[38:41], v[180:183], v[220:223], v[38:41]
	v_mfma_f32_16x16x32_bf16 v[34:37], v[204:207], v[220:223], v[34:37]
	v_mfma_f32_16x16x32_bf16 v[22:25], v[180:183], v[228:231], v[22:25]
	v_mfma_f32_16x16x32_bf16 v[18:21], v[204:207], v[228:231], v[18:21]
	v_mfma_f32_16x16x32_bf16 v[6:9], v[180:183], v[236:239], v[6:9]
	v_mfma_f32_16x16x32_bf16 v[2:5], v[204:207], v[236:239], v[2:5]
	s_setprio 0
	s_barrier
	s_add_i32 s67, s67, 2
	s_add_u32 s36, s36, 0x100
	s_addc_u32 s37, s37, 0
	s_add_u32 s62, s62, 0x100
	s_addc_u32 s63, s63, 0
	s_cmp_gt_u32 s67, 29
	s_cbranch_scc0 .LBB0_281
	s_and_b64 vcc, exec, s[4:5]
	s_cbranch_vccnz .LBB0_286
	s_cmp_lt_i32 s57, 30
	s_mov_b64 s[18:19], -1
	s_cbranch_scc1 .LBB0_287
